# hand-written lean epilogues for in-proj/gate (plain+sigmoid), up (relu^2) and gated-branch-merge GEMMs: second-half operand loads issued before first-half stores, interleaved exact rstd chains, first-
# baseline (speedup 1.0000x reference)
; __device__ __forceinline__ unsigned cvt_pk_bf16(float lo, float hi) { unsigned r; asm volatile("v_cvt_pk_bf16_f32 %0, %1, %2" : "=v"(r) : "v"(lo), "v"(hi)); return r; }
; #define GAS __attribute__((address_space(1)))
; DI int lane_id_opaque() { int l; asm volatile("v_mbcnt_lo_u32_b32 %0, -1, 0\n\tv_mbcnt_hi_u32_b32 %0, -1, %0" : "=v"(l)); return l; }
;     DI void operator()(AccRef acc, const pg8::Unit& u, int wr, int wc, int, int) const {
;         const int lane_ = lane_id_opaque(), fr = lane_ & 15, fq = lane_ >> 4;
;         EPI_PRELOAD_RSTD(ssq)
;         EPI_ROWS_BEGIN
;             const float rs = rs8[ai * 4 + m];
;             EPI_COLS_BEGIN
;                 {
;                     const f32x4 z4 = {0.f, 0.f, 0.f, 0.f}; const float rs2 = rs * rs;
;                     const f32x4 m0 = __builtin_elementwise_max(v0, z4), m1 = __builtin_elementwise_max(v1, z4);
;                     v0 = (v0 * m0) * rs2; v1 = (v1 * m1) * rs2;
;                 }
;                 u32x4 w; w.x = cvt_pk_bf16(v0[0], v0[1]); w.y = cvt_pk_bf16(v0[2], v0[3]); w.z = cvt_pk_bf16(v1[0], v1[1]); w.w = cvt_pk_bf16(v1[2], v1[3]);
;                 *(GAS u32x4*)(U + (size_t)lrow * UP + col) = w;
;             EPI_END
;         EPI_ROW_END
;     }
.Llean_C_entry:
	v_mbcnt_lo_u32_b32 v128, -1, 0
	v_mbcnt_hi_u32_b32 v128, -1, v128
	v_and_b32_e32 v129, 15, v128
	v_lshrrev_b32_e32 v130, 4, v128
	v_or_b32_e32 v129, s49, v129
	v_lshl_add_u32 v131, s88, 8, v129
	v_lshlrev_b32_e32 v132, 4, v130
	v_lshl_add_u32 v132, v131, 6, v132
	v_add_u32_e32 v132, 0x2000, v132
	v_mov_b32_e32 v133, 0
	v_lshl_add_u64 v[136:137], s[60:61], 0, v[132:133]
	global_load_dwordx4 v[140:143], v[136:137], off
	global_load_dwordx4 v[144:147], v[136:137], off offset:1024
	global_load_dwordx4 v[148:151], v[136:137], off offset:2048
	global_load_dwordx4 v[152:155], v[136:137], off offset:3072
	v_readlane_b32 s4, v253, 51
	v_readlane_b32 s5, v253, 52
	v_mul_lo_u32 v196, v131, s43
	v_mov_b32_e32 v197, 0
	s_lshl_b32 s2, s80, 8
	s_or_b32 s2, s2, s62
	v_lshl_add_u32 v138, v130, 3, s2
	v_lshlrev_b32_e32 v138, 1, v138
	v_mov_b32_e32 v139, 0
	v_lshl_add_u64 v[196:197], v[196:197], 0, s[4:5]
	v_lshl_add_u64 v[196:197], v[196:197], 0, v[138:139]
	s_mov_b32 s2, 0x20800
	s_mov_b32 s3, 0
	s_mov_b32 s30, 0xa2800
	s_mov_b32 s31, 0
	v_mov_b32_e32 v195, 0x260
	v_add_f32_e32 v208, v224, v225
	v_add_f32_e32 v209, v226, v227
	v_add_f32_e32 v208, v208, v209
	v_add_f32_e32 v210, v228, v229
	v_add_f32_e32 v211, v230, v231
	v_add_f32_e32 v210, v210, v211
	v_add_f32_e32 v212, v232, v233
	v_add_f32_e32 v213, v234, v235
	v_add_f32_e32 v212, v212, v213
	v_add_f32_e32 v214, v236, v237
	v_add_f32_e32 v215, v238, v239
	v_add_f32_e32 v214, v214, v215
	ds_swizzle_b32 v209, v208 offset:swizzle(SWAP,16)
	ds_swizzle_b32 v211, v210 offset:swizzle(SWAP,16)
	ds_swizzle_b32 v213, v212 offset:swizzle(SWAP,16)
	ds_swizzle_b32 v215, v214 offset:swizzle(SWAP,16)
	s_waitcnt lgkmcnt(0)
	v_add_f32_e32 v208, v208, v209
	v_add_f32_e32 v210, v210, v211
	v_add_f32_e32 v212, v212, v213
	v_add_f32_e32 v214, v214, v215
	v_mov_b32_e32 v209, v208
	v_mov_b32_e32 v211, v210
	v_mov_b32_e32 v213, v212
	v_mov_b32_e32 v215, v214
	s_nop 1
	v_permlane32_swap_b32_e32 v208, v209
	v_permlane32_swap_b32_e32 v210, v211
	v_permlane32_swap_b32_e32 v212, v213
	v_permlane32_swap_b32_e32 v214, v215
	v_add_f32_e32 v208, v208, v209
	v_add_f32_e32 v210, v210, v211
	v_add_f32_e32 v212, v212, v213
	v_add_f32_e32 v214, v214, v215
	v_fmamk_f32 v208, v208, 0x3a800000, v246
	v_fmamk_f32 v210, v210, 0x3a800000, v246
	v_sqrt_f32_e32 v188, v208
	v_sqrt_f32_e32 v166, v210
	v_add_u32_e32 v189, -1, v188
	v_add_u32_e32 v167, -1, v166
	v_fma_f32 v190, -v189, v188, v208
	v_fma_f32 v168, -v167, v166, v210
	v_cmp_ge_f32_e64 s[98:99], 0, v190
	v_cmp_ge_f32_e64 s[4:5], 0, v168
	v_add_u32_e32 v190, 1, v188
	v_add_u32_e32 v168, 1, v166
	v_cndmask_b32_e64 v189, v188, v189, s[98:99]
	v_cndmask_b32_e64 v167, v166, v167, s[4:5]
	v_fma_f32 v191, -v190, v188, v208
	v_fma_f32 v169, -v168, v166, v210
	v_cmp_lt_f32_e64 s[98:99], 0, v191
	v_cmp_lt_f32_e64 s[4:5], 0, v169
	s_nop 0
	v_cndmask_b32_e64 v188, v189, v190, s[98:99]
	v_cndmask_b32_e64 v166, v167, v168, s[4:5]
	v_rcp_f32_e32 v189, v188
	v_rcp_f32_e32 v167, v166
	v_fma_f32 v190, -v188, v189, 1.0
	v_fma_f32 v168, -v166, v167, 1.0
	v_fmac_f32_e32 v189, v190, v189
	v_fmac_f32_e32 v167, v168, v167
	v_fma_f32 v194, -v188, v189, 1.0
	v_fma_f32 v170, -v166, v167, 1.0
	v_fma_f32 v191, v194, v189, v189
	v_fma_f32 v169, v170, v167, v167
	v_fma_f32 v194, -v188, v191, 1.0
	v_fma_f32 v170, -v166, v169, 1.0
	v_fma_f32 v208, v194, v189, v191
	v_fma_f32 v210, v170, v167, v169
	v_fmamk_f32 v212, v212, 0x3a800000, v246
	v_fmamk_f32 v214, v214, 0x3a800000, v246
	v_sqrt_f32_e32 v188, v212
	v_sqrt_f32_e32 v166, v214
	v_add_u32_e32 v189, -1, v188
	v_add_u32_e32 v167, -1, v166
	v_fma_f32 v190, -v189, v188, v212
	v_fma_f32 v168, -v167, v166, v214
	v_cmp_ge_f32_e64 s[98:99], 0, v190
	v_cmp_ge_f32_e64 s[4:5], 0, v168
	v_add_u32_e32 v190, 1, v188
	v_add_u32_e32 v168, 1, v166
	v_cndmask_b32_e64 v189, v188, v189, s[98:99]
	v_cndmask_b32_e64 v167, v166, v167, s[4:5]
	v_fma_f32 v191, -v190, v188, v212
	v_fma_f32 v169, -v168, v166, v214
	v_cmp_lt_f32_e64 s[98:99], 0, v191
	v_cmp_lt_f32_e64 s[4:5], 0, v169
	s_nop 0
	v_cndmask_b32_e64 v188, v189, v190, s[98:99]
	v_cndmask_b32_e64 v166, v167, v168, s[4:5]
	v_rcp_f32_e32 v189, v188
	v_rcp_f32_e32 v167, v166
	v_fma_f32 v190, -v188, v189, 1.0
	v_fma_f32 v168, -v166, v167, 1.0
	v_fmac_f32_e32 v189, v190, v189
	v_fmac_f32_e32 v167, v168, v167
	v_fma_f32 v194, -v188, v189, 1.0
	v_fma_f32 v170, -v166, v167, 1.0
	v_fma_f32 v191, v194, v189, v189
	v_fma_f32 v169, v170, v167, v167
	v_fma_f32 v194, -v188, v191, 1.0
	v_fma_f32 v170, -v166, v169, 1.0
	v_fma_f32 v212, v194, v189, v191
	v_fma_f32 v214, v170, v167, v169
	v_mul_f32_e32 v208, v208, v208
	v_mul_f32_e32 v210, v210, v210
	v_mul_f32_e32 v212, v212, v212
	v_mul_f32_e32 v214, v214, v214
	v_max_f32_e32 v166, 0, v124
	v_max_f32_e32 v167, 0, v125
	v_max_f32_e32 v168, 0, v126
	v_max_f32_e32 v169, 0, v127
	v_max_f32_e32 v170, 0, v120
	v_max_f32_e32 v171, 0, v121
	v_max_f32_e32 v172, 0, v122
	v_max_f32_e32 v173, 0, v123
	v_pk_mul_f32 v[124:125], v[124:125], v[166:167]
	v_pk_mul_f32 v[126:127], v[126:127], v[168:169]
	v_pk_mul_f32 v[120:121], v[120:121], v[170:171]
	v_pk_mul_f32 v[122:123], v[122:123], v[172:173]
	v_pk_mul_f32 v[124:125], v[124:125], v[208:209] op_sel_hi:[1,0]
	v_pk_mul_f32 v[126:127], v[126:127], v[208:209] op_sel_hi:[1,0]
	v_pk_mul_f32 v[120:121], v[120:121], v[208:209] op_sel_hi:[1,0]
	v_pk_mul_f32 v[122:123], v[122:123], v[208:209] op_sel_hi:[1,0]
	v_cvt_pk_bf16_f32 v174, v124, v125
	v_cvt_pk_bf16_f32 v175, v126, v127
	v_cvt_pk_bf16_f32 v176, v120, v121
	v_cvt_pk_bf16_f32 v177, v122, v123
	global_store_dwordx4 v[196:197], v[174:177], off
	v_max_f32_e32 v166, 0, v116
	v_max_f32_e32 v167, 0, v117
; __device__ __forceinline__ unsigned cvt_pk_bf16(float lo, float hi) { unsigned r; asm volatile("v_cvt_pk_bf16_f32 %0, %1, %2" : "=v"(r) : "v"(lo), "v"(hi)); return r; }
; #define GAS __attribute__((address_space(1)))
;     DI void operator()(AccRef acc, const pg8::Unit& u, int wr, int wc, int, int) const {
;     ...
;                     const f32x4 z4 = {0.f, 0.f, 0.f, 0.f}; const float rs2 = rs * rs;
;                     const f32x4 m0 = __builtin_elementwise_max(v0, z4), m1 = __builtin_elementwise_max(v1, z4);
;                     v0 = (v0 * m0) * rs2; v1 = (v1 * m1) * rs2;
;                 }
;                 u32x4 w; w.x = cvt_pk_bf16(v0[0], v0[1]); w.y = cvt_pk_bf16(v0[2], v0[3]); w.z = cvt_pk_bf16(v1[0], v1[1]); w.w = cvt_pk_bf16(v1[2], v1[3]);
;                 *(GAS u32x4*)(U + (size_t)lrow * UP + col) = w;
	v_max_f32_e32 v168, 0, v118
	v_max_f32_e32 v169, 0, v119
	v_max_f32_e32 v170, 0, v112
	v_max_f32_e32 v171, 0, v113
	v_max_f32_e32 v172, 0, v114
	v_max_f32_e32 v173, 0, v115
	v_pk_mul_f32 v[116:117], v[116:117], v[166:167]
	v_pk_mul_f32 v[118:119], v[118:119], v[168:169]
	v_pk_mul_f32 v[112:113], v[112:113], v[170:171]
	v_pk_mul_f32 v[114:115], v[114:115], v[172:173]
	v_pk_mul_f32 v[116:117], v[116:117], v[208:209] op_sel_hi:[1,0]
	v_pk_mul_f32 v[118:119], v[118:119], v[208:209] op_sel_hi:[1,0]
	v_pk_mul_f32 v[112:113], v[112:113], v[208:209] op_sel_hi:[1,0]
	v_pk_mul_f32 v[114:115], v[114:115], v[208:209] op_sel_hi:[1,0]
	v_cvt_pk_bf16_f32 v178, v116, v117
	v_cvt_pk_bf16_f32 v179, v118, v119
	v_cvt_pk_bf16_f32 v180, v112, v113
	v_cvt_pk_bf16_f32 v181, v114, v115
	global_store_dwordx4 v[196:197], v[178:181], off offset:256
	v_lshl_add_u64 v[244:245], v[196:197], 0, s[2:3]
	v_max_f32_e32 v166, 0, v108
	v_max_f32_e32 v167, 0, v109
	v_max_f32_e32 v168, 0, v110
	v_max_f32_e32 v169, 0, v111
	v_max_f32_e32 v170, 0, v104
	v_max_f32_e32 v171, 0, v105
	v_max_f32_e32 v172, 0, v106
	v_max_f32_e32 v173, 0, v107
	v_pk_mul_f32 v[108:109], v[108:109], v[166:167]
	v_pk_mul_f32 v[110:111], v[110:111], v[168:169]
	v_pk_mul_f32 v[104:105], v[104:105], v[170:171]
	v_pk_mul_f32 v[106:107], v[106:107], v[172:173]
	v_pk_mul_f32 v[108:109], v[108:109], v[210:211] op_sel_hi:[1,0]
	v_pk_mul_f32 v[110:111], v[110:111], v[210:211] op_sel_hi:[1,0]
	v_pk_mul_f32 v[104:105], v[104:105], v[210:211] op_sel_hi:[1,0]
	v_pk_mul_f32 v[106:107], v[106:107], v[210:211] op_sel_hi:[1,0]
	v_cvt_pk_bf16_f32 v174, v108, v109
	v_cvt_pk_bf16_f32 v175, v110, v111
	v_cvt_pk_bf16_f32 v176, v104, v105
	v_cvt_pk_bf16_f32 v177, v106, v107
	global_store_dwordx4 v[244:245], v[174:177], off
	v_max_f32_e32 v166, 0, v100
	v_max_f32_e32 v167, 0, v101
	v_max_f32_e32 v168, 0, v102
	v_max_f32_e32 v169, 0, v103
	v_max_f32_e32 v170, 0, v96
	v_max_f32_e32 v171, 0, v97
	v_max_f32_e32 v172, 0, v98
	v_max_f32_e32 v173, 0, v99
	v_pk_mul_f32 v[100:101], v[100:101], v[166:167]
	v_pk_mul_f32 v[102:103], v[102:103], v[168:169]
	v_pk_mul_f32 v[96:97], v[96:97], v[170:171]
	v_pk_mul_f32 v[98:99], v[98:99], v[172:173]
	v_pk_mul_f32 v[100:101], v[100:101], v[210:211] op_sel_hi:[1,0]
	v_pk_mul_f32 v[102:103], v[102:103], v[210:211] op_sel_hi:[1,0]
	v_pk_mul_f32 v[96:97], v[96:97], v[210:211] op_sel_hi:[1,0]
	v_pk_mul_f32 v[98:99], v[98:99], v[210:211] op_sel_hi:[1,0]
	v_cvt_pk_bf16_f32 v178, v100, v101
	v_cvt_pk_bf16_f32 v179, v102, v103
	v_cvt_pk_bf16_f32 v180, v96, v97
	v_cvt_pk_bf16_f32 v181, v98, v99
	global_store_dwordx4 v[244:245], v[178:181], off offset:256
	v_lshl_add_u64 v[196:197], v[244:245], 0, s[2:3]
	v_max_f32_e32 v166, 0, v92
	v_max_f32_e32 v167, 0, v93
	v_max_f32_e32 v168, 0, v94
	v_max_f32_e32 v169, 0, v95
	v_max_f32_e32 v170, 0, v88
	v_max_f32_e32 v171, 0, v89
	v_max_f32_e32 v172, 0, v90
	v_max_f32_e32 v173, 0, v91
	v_pk_mul_f32 v[92:93], v[92:93], v[166:167]
	v_pk_mul_f32 v[94:95], v[94:95], v[168:169]
	v_pk_mul_f32 v[88:89], v[88:89], v[170:171]
	v_pk_mul_f32 v[90:91], v[90:91], v[172:173]
	v_pk_mul_f32 v[92:93], v[92:93], v[212:213] op_sel_hi:[1,0]
	v_pk_mul_f32 v[94:95], v[94:95], v[212:213] op_sel_hi:[1,0]
	v_pk_mul_f32 v[88:89], v[88:89], v[212:213] op_sel_hi:[1,0]
	v_pk_mul_f32 v[90:91], v[90:91], v[212:213] op_sel_hi:[1,0]
	v_cvt_pk_bf16_f32 v174, v92, v93
	v_cvt_pk_bf16_f32 v175, v94, v95
	v_cvt_pk_bf16_f32 v176, v88, v89
	v_cvt_pk_bf16_f32 v177, v90, v91
	global_store_dwordx4 v[196:197], v[174:177], off
	v_max_f32_e32 v166, 0, v84
	v_max_f32_e32 v167, 0, v85
	v_max_f32_e32 v168, 0, v86
	v_max_f32_e32 v169, 0, v87
	v_max_f32_e32 v170, 0, v80
	v_max_f32_e32 v171, 0, v81
	v_max_f32_e32 v172, 0, v82
	v_max_f32_e32 v173, 0, v83
	v_pk_mul_f32 v[84:85], v[84:85], v[166:167]
	v_pk_mul_f32 v[86:87], v[86:87], v[168:169]
	v_pk_mul_f32 v[80:81], v[80:81], v[170:171]
	v_pk_mul_f32 v[82:83], v[82:83], v[172:173]
	v_pk_mul_f32 v[84:85], v[84:85], v[212:213] op_sel_hi:[1,0]
	v_pk_mul_f32 v[86:87], v[86:87], v[212:213] op_sel_hi:[1,0]
	v_pk_mul_f32 v[80:81], v[80:81], v[212:213] op_sel_hi:[1,0]
	v_pk_mul_f32 v[82:83], v[82:83], v[212:213] op_sel_hi:[1,0]
	v_cvt_pk_bf16_f32 v178, v84, v85
	v_cvt_pk_bf16_f32 v179, v86, v87
	v_cvt_pk_bf16_f32 v180, v80, v81
	v_cvt_pk_bf16_f32 v181, v82, v83
	global_store_dwordx4 v[196:197], v[178:181], off offset:256
	v_lshl_add_u64 v[244:245], v[196:197], 0, s[2:3]
	v_max_f32_e32 v166, 0, v76
	v_max_f32_e32 v167, 0, v77
	v_max_f32_e32 v168, 0, v78
	v_max_f32_e32 v169, 0, v79
	v_max_f32_e32 v170, 0, v72
	v_max_f32_e32 v171, 0, v73
	v_max_f32_e32 v172, 0, v74
	v_max_f32_e32 v173, 0, v75
	v_pk_mul_f32 v[76:77], v[76:77], v[166:167]
	v_pk_mul_f32 v[78:79], v[78:79], v[168:169]
	v_pk_mul_f32 v[72:73], v[72:73], v[170:171]
	v_pk_mul_f32 v[74:75], v[74:75], v[172:173]
	v_pk_mul_f32 v[76:77], v[76:77], v[214:215] op_sel_hi:[1,0]
	v_pk_mul_f32 v[78:79], v[78:79], v[214:215] op_sel_hi:[1,0]
	v_pk_mul_f32 v[72:73], v[72:73], v[214:215] op_sel_hi:[1,0]
	v_pk_mul_f32 v[74:75], v[74:75], v[214:215] op_sel_hi:[1,0]
	v_cvt_pk_bf16_f32 v174, v76, v77
	v_cvt_pk_bf16_f32 v175, v78, v79
	v_cvt_pk_bf16_f32 v176, v72, v73
	v_cvt_pk_bf16_f32 v177, v74, v75
	global_store_dwordx4 v[244:245], v[174:177], off
	v_max_f32_e32 v166, 0, v68
	v_max_f32_e32 v167, 0, v69
	v_max_f32_e32 v168, 0, v70
	v_max_f32_e32 v169, 0, v71
	v_max_f32_e32 v170, 0, v64
	v_max_f32_e32 v171, 0, v65
	v_max_f32_e32 v172, 0, v66
	v_max_f32_e32 v173, 0, v67
	v_pk_mul_f32 v[68:69], v[68:69], v[166:167]
	v_pk_mul_f32 v[70:71], v[70:71], v[168:169]
	v_pk_mul_f32 v[64:65], v[64:65], v[170:171]
	v_pk_mul_f32 v[66:67], v[66:67], v[172:173]
	v_pk_mul_f32 v[68:69], v[68:69], v[214:215] op_sel_hi:[1,0]
	v_pk_mul_f32 v[70:71], v[70:71], v[214:215] op_sel_hi:[1,0]
	v_pk_mul_f32 v[64:65], v[64:65], v[214:215] op_sel_hi:[1,0]
	v_pk_mul_f32 v[66:67], v[66:67], v[214:215] op_sel_hi:[1,0]
	v_cvt_pk_bf16_f32 v178, v68, v69
	v_cvt_pk_bf16_f32 v179, v70, v71
	v_cvt_pk_bf16_f32 v180, v64, v65
	v_cvt_pk_bf16_f32 v181, v66, v67
	global_store_dwordx4 v[244:245], v[178:181], off offset:256
	v_lshl_add_u64 v[196:197], v[244:245], 0, s[30:31]
	s_waitcnt vmcnt(8)
; __device__ __forceinline__ unsigned cvt_pk_bf16(float lo, float hi) { unsigned r; asm volatile("v_cvt_pk_bf16_f32 %0, %1, %2" : "=v"(r) : "v"(lo), "v"(hi)); return r; }
; #define GAS __attribute__((address_space(1)))
;     DI void operator()(AccRef acc, const pg8::Unit& u, int wr, int wc, int, int) const {
;     ...
;             const float rs = rs8[ai * 4 + m];
;             EPI_COLS_BEGIN
;                 {
;                     const f32x4 z4 = {0.f, 0.f, 0.f, 0.f}; const float rs2 = rs * rs;
;                     const f32x4 m0 = __builtin_elementwise_max(v0, z4), m1 = __builtin_elementwise_max(v1, z4);
;                     v0 = (v0 * m0) * rs2; v1 = (v1 * m1) * rs2;
;                 }
;                 u32x4 w; w.x = cvt_pk_bf16(v0[0], v0[1]); w.y = cvt_pk_bf16(v0[2], v0[3]); w.z = cvt_pk_bf16(v1[0], v1[1]); w.w = cvt_pk_bf16(v1[2], v1[3]);
;                 *(GAS u32x4*)(U + (size_t)lrow * UP + col) = w;
	v_add_f32_e32 v216, v140, v141
	v_add_f32_e32 v217, v142, v143
	v_add_f32_e32 v216, v216, v217
	v_add_f32_e32 v218, v144, v145
	v_add_f32_e32 v219, v146, v147
	v_add_f32_e32 v218, v218, v219
	v_add_f32_e32 v184, v148, v149
	v_add_f32_e32 v185, v150, v151
	v_add_f32_e32 v184, v184, v185
	v_add_f32_e32 v186, v152, v153
	v_add_f32_e32 v187, v154, v155
	v_add_f32_e32 v186, v186, v187
	ds_swizzle_b32 v217, v216 offset:swizzle(SWAP,16)
	ds_swizzle_b32 v219, v218 offset:swizzle(SWAP,16)
	ds_swizzle_b32 v185, v184 offset:swizzle(SWAP,16)
	ds_swizzle_b32 v187, v186 offset:swizzle(SWAP,16)
	s_waitcnt lgkmcnt(0)
	v_add_f32_e32 v216, v216, v217
	v_add_f32_e32 v218, v218, v219
	v_add_f32_e32 v184, v184, v185
	v_add_f32_e32 v186, v186, v187
	v_mov_b32_e32 v217, v216
	v_mov_b32_e32 v219, v218
	v_mov_b32_e32 v185, v184
	v_mov_b32_e32 v187, v186
	s_nop 1
	v_permlane32_swap_b32_e32 v216, v217
	v_permlane32_swap_b32_e32 v218, v219
	v_permlane32_swap_b32_e32 v184, v185
	v_permlane32_swap_b32_e32 v186, v187
	v_add_f32_e32 v216, v216, v217
	v_add_f32_e32 v218, v218, v219
	v_add_f32_e32 v184, v184, v185
	v_add_f32_e32 v186, v186, v187
	v_fmamk_f32 v216, v216, 0x3a800000, v246
	v_fmamk_f32 v218, v218, 0x3a800000, v246
	v_sqrt_f32_e32 v188, v216
	v_sqrt_f32_e32 v166, v218
	v_add_u32_e32 v189, -1, v188
	v_add_u32_e32 v167, -1, v166
	v_fma_f32 v190, -v189, v188, v216
	v_fma_f32 v168, -v167, v166, v218
	v_cmp_ge_f32_e64 s[98:99], 0, v190
	v_cmp_ge_f32_e64 s[4:5], 0, v168
	v_add_u32_e32 v190, 1, v188
	v_add_u32_e32 v168, 1, v166
	v_cndmask_b32_e64 v189, v188, v189, s[98:99]
	v_cndmask_b32_e64 v167, v166, v167, s[4:5]
	v_fma_f32 v191, -v190, v188, v216
	v_fma_f32 v169, -v168, v166, v218
	v_cmp_lt_f32_e64 s[98:99], 0, v191
	v_cmp_lt_f32_e64 s[4:5], 0, v169
	s_nop 0
	v_cndmask_b32_e64 v188, v189, v190, s[98:99]
	v_cndmask_b32_e64 v166, v167, v168, s[4:5]
	v_rcp_f32_e32 v189, v188
	v_rcp_f32_e32 v167, v166
	v_fma_f32 v190, -v188, v189, 1.0
	v_fma_f32 v168, -v166, v167, 1.0
	v_fmac_f32_e32 v189, v190, v189
	v_fmac_f32_e32 v167, v168, v167
	v_fma_f32 v194, -v188, v189, 1.0
	v_fma_f32 v170, -v166, v167, 1.0
	v_fma_f32 v191, v194, v189, v189
	v_fma_f32 v169, v170, v167, v167
	v_fma_f32 v194, -v188, v191, 1.0
	v_fma_f32 v170, -v166, v169, 1.0
	v_fma_f32 v216, v194, v189, v191
	v_fma_f32 v218, v170, v167, v169
	v_fmamk_f32 v184, v184, 0x3a800000, v246
	v_fmamk_f32 v186, v186, 0x3a800000, v246
	v_sqrt_f32_e32 v188, v184
	v_sqrt_f32_e32 v166, v186
	v_add_u32_e32 v189, -1, v188
	v_add_u32_e32 v167, -1, v166
	v_fma_f32 v190, -v189, v188, v184
	v_fma_f32 v168, -v167, v166, v186
	v_cmp_ge_f32_e64 s[98:99], 0, v190
	v_cmp_ge_f32_e64 s[4:5], 0, v168
	v_add_u32_e32 v190, 1, v188
	v_add_u32_e32 v168, 1, v166
	v_cndmask_b32_e64 v189, v188, v189, s[98:99]
	v_cndmask_b32_e64 v167, v166, v167, s[4:5]
	v_fma_f32 v191, -v190, v188, v184
	v_fma_f32 v169, -v168, v166, v186
	v_cmp_lt_f32_e64 s[98:99], 0, v191
	v_cmp_lt_f32_e64 s[4:5], 0, v169
	s_nop 0
	v_cndmask_b32_e64 v188, v189, v190, s[98:99]
	v_cndmask_b32_e64 v166, v167, v168, s[4:5]
	v_rcp_f32_e32 v189, v188
	v_rcp_f32_e32 v167, v166
	v_fma_f32 v190, -v188, v189, 1.0
	v_fma_f32 v168, -v166, v167, 1.0
	v_fmac_f32_e32 v189, v190, v189
	v_fmac_f32_e32 v167, v168, v167
	v_fma_f32 v194, -v188, v189, 1.0
	v_fma_f32 v170, -v166, v167, 1.0
	v_fma_f32 v191, v194, v189, v189
	v_fma_f32 v169, v170, v167, v167
	v_fma_f32 v194, -v188, v191, 1.0
	v_fma_f32 v170, -v166, v169, 1.0
	v_fma_f32 v184, v194, v189, v191
	v_fma_f32 v186, v170, v167, v169
	v_mul_f32_e32 v216, v216, v216
	v_mul_f32_e32 v218, v218, v218
	v_mul_f32_e32 v184, v184, v184
	v_mul_f32_e32 v186, v186, v186
	v_max_f32_e32 v166, 0, v60
	v_max_f32_e32 v167, 0, v61
	v_max_f32_e32 v168, 0, v62
	v_max_f32_e32 v169, 0, v63
	v_max_f32_e32 v170, 0, v56
	v_max_f32_e32 v171, 0, v57
	v_max_f32_e32 v172, 0, v58
	v_max_f32_e32 v173, 0, v59
	v_pk_mul_f32 v[60:61], v[60:61], v[166:167]
	v_pk_mul_f32 v[62:63], v[62:63], v[168:169]
	v_pk_mul_f32 v[56:57], v[56:57], v[170:171]
	v_pk_mul_f32 v[58:59], v[58:59], v[172:173]
	v_pk_mul_f32 v[60:61], v[60:61], v[216:217] op_sel_hi:[1,0]
	v_pk_mul_f32 v[62:63], v[62:63], v[216:217] op_sel_hi:[1,0]
	v_pk_mul_f32 v[56:57], v[56:57], v[216:217] op_sel_hi:[1,0]
	v_pk_mul_f32 v[58:59], v[58:59], v[216:217] op_sel_hi:[1,0]
	v_cvt_pk_bf16_f32 v174, v60, v61
	v_cvt_pk_bf16_f32 v175, v62, v63
	v_cvt_pk_bf16_f32 v176, v56, v57
	v_cvt_pk_bf16_f32 v177, v58, v59
	global_store_dwordx4 v[196:197], v[174:177], off
	v_max_f32_e32 v166, 0, v52
	v_max_f32_e32 v167, 0, v53
	v_max_f32_e32 v168, 0, v54
	v_max_f32_e32 v169, 0, v55
	v_max_f32_e32 v170, 0, v48
	v_max_f32_e32 v171, 0, v49
	v_max_f32_e32 v172, 0, v50
	v_max_f32_e32 v173, 0, v51
	v_pk_mul_f32 v[52:53], v[52:53], v[166:167]
	v_pk_mul_f32 v[54:55], v[54:55], v[168:169]
	v_pk_mul_f32 v[48:49], v[48:49], v[170:171]
	v_pk_mul_f32 v[50:51], v[50:51], v[172:173]
	v_pk_mul_f32 v[52:53], v[52:53], v[216:217] op_sel_hi:[1,0]
	v_pk_mul_f32 v[54:55], v[54:55], v[216:217] op_sel_hi:[1,0]
	v_pk_mul_f32 v[48:49], v[48:49], v[216:217] op_sel_hi:[1,0]
	v_pk_mul_f32 v[50:51], v[50:51], v[216:217] op_sel_hi:[1,0]
	v_cvt_pk_bf16_f32 v178, v52, v53
	v_cvt_pk_bf16_f32 v179, v54, v55
	v_cvt_pk_bf16_f32 v180, v48, v49
	v_cvt_pk_bf16_f32 v181, v50, v51
	global_store_dwordx4 v[196:197], v[178:181], off offset:256
; __device__ __forceinline__ unsigned cvt_pk_bf16(float lo, float hi) { unsigned r; asm volatile("v_cvt_pk_bf16_f32 %0, %1, %2" : "=v"(r) : "v"(lo), "v"(hi)); return r; }
; #define GAS __attribute__((address_space(1)))
;     DI void operator()(AccRef acc, const pg8::Unit& u, int wr, int wc, int, int) const {
;     ...
;                     const f32x4 z4 = {0.f, 0.f, 0.f, 0.f}; const float rs2 = rs * rs;
;                     const f32x4 m0 = __builtin_elementwise_max(v0, z4), m1 = __builtin_elementwise_max(v1, z4);
;                     v0 = (v0 * m0) * rs2; v1 = (v1 * m1) * rs2;
;                 }
;                 u32x4 w; w.x = cvt_pk_bf16(v0[0], v0[1]); w.y = cvt_pk_bf16(v0[2], v0[3]); w.z = cvt_pk_bf16(v1[0], v1[1]); w.w = cvt_pk_bf16(v1[2], v1[3]);
;                 *(GAS u32x4*)(U + (size_t)lrow * UP + col) = w;
	v_lshl_add_u64 v[244:245], v[196:197], 0, s[2:3]
	v_max_f32_e32 v166, 0, v44
	v_max_f32_e32 v167, 0, v45
	v_max_f32_e32 v168, 0, v46
	v_max_f32_e32 v169, 0, v47
	v_max_f32_e32 v170, 0, v40
	v_max_f32_e32 v171, 0, v41
	v_max_f32_e32 v172, 0, v42
	v_max_f32_e32 v173, 0, v43
	v_pk_mul_f32 v[44:45], v[44:45], v[166:167]
	v_pk_mul_f32 v[46:47], v[46:47], v[168:169]
	v_pk_mul_f32 v[40:41], v[40:41], v[170:171]
	v_pk_mul_f32 v[42:43], v[42:43], v[172:173]
	v_pk_mul_f32 v[44:45], v[44:45], v[218:219] op_sel_hi:[1,0]
	v_pk_mul_f32 v[46:47], v[46:47], v[218:219] op_sel_hi:[1,0]
	v_pk_mul_f32 v[40:41], v[40:41], v[218:219] op_sel_hi:[1,0]
	v_pk_mul_f32 v[42:43], v[42:43], v[218:219] op_sel_hi:[1,0]
	v_cvt_pk_bf16_f32 v174, v44, v45
	v_cvt_pk_bf16_f32 v175, v46, v47
	v_cvt_pk_bf16_f32 v176, v40, v41
	v_cvt_pk_bf16_f32 v177, v42, v43
	global_store_dwordx4 v[244:245], v[174:177], off
	v_max_f32_e32 v166, 0, v36
	v_max_f32_e32 v167, 0, v37
	v_max_f32_e32 v168, 0, v38
	v_max_f32_e32 v169, 0, v39
	v_max_f32_e32 v170, 0, v32
	v_max_f32_e32 v171, 0, v33
	v_max_f32_e32 v172, 0, v34
	v_max_f32_e32 v173, 0, v35
	v_pk_mul_f32 v[36:37], v[36:37], v[166:167]
	v_pk_mul_f32 v[38:39], v[38:39], v[168:169]
	v_pk_mul_f32 v[32:33], v[32:33], v[170:171]
	v_pk_mul_f32 v[34:35], v[34:35], v[172:173]
	v_pk_mul_f32 v[36:37], v[36:37], v[218:219] op_sel_hi:[1,0]
	v_pk_mul_f32 v[38:39], v[38:39], v[218:219] op_sel_hi:[1,0]
	v_pk_mul_f32 v[32:33], v[32:33], v[218:219] op_sel_hi:[1,0]
	v_pk_mul_f32 v[34:35], v[34:35], v[218:219] op_sel_hi:[1,0]
	v_cvt_pk_bf16_f32 v178, v36, v37
	v_cvt_pk_bf16_f32 v179, v38, v39
	v_cvt_pk_bf16_f32 v180, v32, v33
	v_cvt_pk_bf16_f32 v181, v34, v35
	global_store_dwordx4 v[244:245], v[178:181], off offset:256
	v_lshl_add_u64 v[196:197], v[244:245], 0, s[2:3]
	v_max_f32_e32 v166, 0, v28
	v_max_f32_e32 v167, 0, v29
	v_max_f32_e32 v168, 0, v30
	v_max_f32_e32 v169, 0, v31
	v_max_f32_e32 v170, 0, v24
	v_max_f32_e32 v171, 0, v25
	v_max_f32_e32 v172, 0, v26
	v_max_f32_e32 v173, 0, v27
	v_pk_mul_f32 v[28:29], v[28:29], v[166:167]
	v_pk_mul_f32 v[30:31], v[30:31], v[168:169]
	v_pk_mul_f32 v[24:25], v[24:25], v[170:171]
	v_pk_mul_f32 v[26:27], v[26:27], v[172:173]
	v_pk_mul_f32 v[28:29], v[28:29], v[184:185] op_sel_hi:[1,0]
	v_pk_mul_f32 v[30:31], v[30:31], v[184:185] op_sel_hi:[1,0]
	v_pk_mul_f32 v[24:25], v[24:25], v[184:185] op_sel_hi:[1,0]
	v_pk_mul_f32 v[26:27], v[26:27], v[184:185] op_sel_hi:[1,0]
	v_cvt_pk_bf16_f32 v174, v28, v29
	v_cvt_pk_bf16_f32 v175, v30, v31
	v_cvt_pk_bf16_f32 v176, v24, v25
	v_cvt_pk_bf16_f32 v177, v26, v27
	global_store_dwordx4 v[196:197], v[174:177], off
	v_max_f32_e32 v166, 0, v20
	v_max_f32_e32 v167, 0, v21
	v_max_f32_e32 v168, 0, v22
	v_max_f32_e32 v169, 0, v23
	v_max_f32_e32 v170, 0, v16
	v_max_f32_e32 v171, 0, v17
	v_max_f32_e32 v172, 0, v18
	v_max_f32_e32 v173, 0, v19
	v_pk_mul_f32 v[20:21], v[20:21], v[166:167]
	v_pk_mul_f32 v[22:23], v[22:23], v[168:169]
	v_pk_mul_f32 v[16:17], v[16:17], v[170:171]
	v_pk_mul_f32 v[18:19], v[18:19], v[172:173]
	v_pk_mul_f32 v[20:21], v[20:21], v[184:185] op_sel_hi:[1,0]
	v_pk_mul_f32 v[22:23], v[22:23], v[184:185] op_sel_hi:[1,0]
	v_pk_mul_f32 v[16:17], v[16:17], v[184:185] op_sel_hi:[1,0]
	v_pk_mul_f32 v[18:19], v[18:19], v[184:185] op_sel_hi:[1,0]
	v_cvt_pk_bf16_f32 v178, v20, v21
	v_cvt_pk_bf16_f32 v179, v22, v23
	v_cvt_pk_bf16_f32 v180, v16, v17
	v_cvt_pk_bf16_f32 v181, v18, v19
	global_store_dwordx4 v[196:197], v[178:181], off offset:256
	v_lshl_add_u64 v[244:245], v[196:197], 0, s[2:3]
	v_max_f32_e32 v166, 0, v12
	v_max_f32_e32 v167, 0, v13
	v_max_f32_e32 v168, 0, v14
	v_max_f32_e32 v169, 0, v15
	v_max_f32_e32 v170, 0, v8
	v_max_f32_e32 v171, 0, v9
	v_max_f32_e32 v172, 0, v10
	v_max_f32_e32 v173, 0, v11
	v_pk_mul_f32 v[12:13], v[12:13], v[166:167]
	v_pk_mul_f32 v[14:15], v[14:15], v[168:169]
	v_pk_mul_f32 v[8:9], v[8:9], v[170:171]
	v_pk_mul_f32 v[10:11], v[10:11], v[172:173]
	v_pk_mul_f32 v[12:13], v[12:13], v[186:187] op_sel_hi:[1,0]
	v_pk_mul_f32 v[14:15], v[14:15], v[186:187] op_sel_hi:[1,0]
	v_pk_mul_f32 v[8:9], v[8:9], v[186:187] op_sel_hi:[1,0]
	v_pk_mul_f32 v[10:11], v[10:11], v[186:187] op_sel_hi:[1,0]
	v_cvt_pk_bf16_f32 v174, v12, v13
	v_cvt_pk_bf16_f32 v175, v14, v15
	v_cvt_pk_bf16_f32 v176, v8, v9
	v_cvt_pk_bf16_f32 v177, v10, v11
	global_store_dwordx4 v[244:245], v[174:177], off
	v_max_f32_e32 v166, 0, v4
	v_max_f32_e32 v167, 0, v5
	v_max_f32_e32 v168, 0, v6
	v_max_f32_e32 v169, 0, v7
	v_max_f32_e32 v170, 0, v0
	v_max_f32_e32 v171, 0, v1
	v_max_f32_e32 v172, 0, v2
	v_max_f32_e32 v173, 0, v3
	v_pk_mul_f32 v[4:5], v[4:5], v[166:167]
	v_pk_mul_f32 v[6:7], v[6:7], v[168:169]
	v_pk_mul_f32 v[0:1], v[0:1], v[170:171]
	v_pk_mul_f32 v[2:3], v[2:3], v[172:173]
	v_pk_mul_f32 v[4:5], v[4:5], v[186:187] op_sel_hi:[1,0]
	v_pk_mul_f32 v[6:7], v[6:7], v[186:187] op_sel_hi:[1,0]
	v_pk_mul_f32 v[0:1], v[0:1], v[186:187] op_sel_hi:[1,0]
	v_pk_mul_f32 v[2:3], v[2:3], v[186:187] op_sel_hi:[1,0]
	v_cvt_pk_bf16_f32 v178, v4, v5
	v_cvt_pk_bf16_f32 v179, v6, v7
	v_cvt_pk_bf16_f32 v180, v0, v1
	v_cvt_pk_bf16_f32 v181, v2, v3
	global_store_dwordx4 v[244:245], v[178:181], off offset:256
	s_andn2_b64 vcc, exec, s[0:1]
	s_mov_b64 s[4:5], -1
	s_cbranch_vccnz .LBB0_685
	s_andn2_b64 vcc, exec, s[10:11]
	s_cbranch_vccnz .LBB0_684
	s_barrier
	s_branch .LBB0_684

; __device__ __forceinline__ unsigned cvt_pk_bf16(float lo, float hi) { unsigned r; asm volatile("v_cvt_pk_bf16_f32 %0, %1, %2" : "=v"(r) : "v"(lo), "v"(hi)); return r; }
; #define GAS __attribute__((address_space(1)))
; DI float bf_lo(unsigned w) { return __uint_as_float(w << 16); }
; DI float bf_hi(unsigned w) { return __uint_as_float(w & 0xffff0000u); }
; DI int lane_id_opaque() { int l; asm volatile("v_mbcnt_lo_u32_b32 %0, -1, 0\n\tv_mbcnt_hi_u32_b32 %0, -1, %0" : "=v"(l)); return l; }
;     DI void operator()(AccRef acc, const pg8::Unit& u, int wr, int wc, int, int) const {
;         const int lane_ = lane_id_opaque(), fr = lane_ & 15, fq = lane_ >> 4;
; #pragma unroll
;         for (int ai = 0; ai < 2; ++ai) {
;             u32x4 gq[4][2], pq[4][2];
; #pragma unroll
;             for (int m = 0; m < 4; ++m)
; #pragma unroll
;                 for (int bj = 0; bj < 2; ++bj) {
;                     const int lrow = u.pm * 256 + ai * 128 + wr * 64 + m * 16 + fr, col = u.pn * 256 + bj * 128 + wc * 32 + 8 * fq;
;                     gq[m][bj] = *(const GAS u32x4*)(G + (size_t)lrow * DM + col);
;                     pq[m][bj] = (u32x4){0u, 0u, 0u, 0u};
;                     if (has_prev) pq[m][bj] = *(const GAS u32x4*)(Mo + (size_t)lrow * ZW + col);
;                 }
;             asm volatile("" ::: "memory");
; #pragma unroll
;             for (int m = 0; m < 4; ++m) {
;                 const int lrow = u.pm * 256 + ai * 128 + wr * 64 + m * 16 + fr;
;                 EPI_COLS_BEGIN
;                     const size_t off = (size_t)lrow * ZW + col;
;                     const u32x4 g = gq[m][bj], p = pq[m][bj];
;                     v0[0] = v0[0] * bf_lo(g.x) + bf_lo(p.x); v0[1] = v0[1] * bf_hi(g.x) + bf_hi(p.x); v0[2] = v0[2] * bf_lo(g.y) + bf_lo(p.y); v0[3] = v0[3] * bf_hi(g.y) + bf_hi(p.y);
;                     v1[0] = v1[0] * bf_lo(g.z) + bf_lo(p.z); v1[1] = v1[1] * bf_hi(g.z) + bf_hi(p.z); v1[2] = v1[2] * bf_lo(g.w) + bf_lo(p.w); v1[3] = v1[3] * bf_hi(g.w) + bf_hi(p.w);
;                     u32x4 w; w.x = cvt_pk_bf16(v0[0], v0[1]); w.y = cvt_pk_bf16(v0[2], v0[3]); w.z = cvt_pk_bf16(v1[0], v1[1]); w.w = cvt_pk_bf16(v1[2], v1[3]);
;                     *(GAS u32x4*)(dummy ? dummy + lane_ * 8 : Mo + off) = w;
.Llean_E_entry:
	v_mbcnt_lo_u32_b32 v224, -1, 0
	v_mbcnt_hi_u32_b32 v224, -1, v224
	v_and_b32_e32 v225, 15, v224
	v_lshrrev_b32_e32 v226, 4, v224
	s_lshl_b32 s2, s92, 8
	s_add_i32 s2, s2, s84
	v_or_b32_e32 v225, s2, v225
	s_lshl_b32 s2, s78, 8
	s_or_b32 s2, s2, s85
	v_lshl_add_u32 v226, v226, 3, s2
	v_lshlrev_b32_e32 v226, 1, v226
	v_lshl_add_u32 v228, v225, 11, v226
	v_mov_b32_e32 v229, 0
	v_lshl_add_u64 v[244:245], s[70:71], 0, v[228:229]
	v_mul_u32_u24_e32 v230, 0x2600, v225
	v_add_u32_e32 v230, v230, v226
	v_mov_b32_e32 v231, 0
	v_lshl_add_u64 v[248:249], s[68:69], 0, v[230:231]
	s_mov_b32 s3, 0
	s_and_b64 vcc, exec, s[6:7]
	s_cbranch_vccnz .Llean_E_hasprev
	v_mov_b32_e32 v160, 0
	v_mov_b32_e32 v161, 0
	v_mov_b32_e32 v162, 0
	v_mov_b32_e32 v163, 0
	v_mov_b32_e32 v164, 0
	v_mov_b32_e32 v165, 0
	v_mov_b32_e32 v166, 0
	v_mov_b32_e32 v167, 0
	v_mov_b32_e32 v168, 0
	v_mov_b32_e32 v169, 0
	v_mov_b32_e32 v170, 0
	v_mov_b32_e32 v171, 0
	v_mov_b32_e32 v172, 0
	v_mov_b32_e32 v173, 0
	v_mov_b32_e32 v174, 0
	v_mov_b32_e32 v175, 0
	v_mov_b32_e32 v176, 0
	v_mov_b32_e32 v177, 0
	v_mov_b32_e32 v178, 0
	v_mov_b32_e32 v179, 0
	v_mov_b32_e32 v180, 0
	v_mov_b32_e32 v181, 0
	v_mov_b32_e32 v182, 0
	v_mov_b32_e32 v183, 0
	v_mov_b32_e32 v184, 0
	v_mov_b32_e32 v185, 0
	v_mov_b32_e32 v186, 0
	v_mov_b32_e32 v187, 0
	v_mov_b32_e32 v188, 0
	v_mov_b32_e32 v189, 0
	v_mov_b32_e32 v190, 0
	v_mov_b32_e32 v191, 0
.Llean_E_hasprev:
	v_mov_b32_e32 v220, v244
	v_mov_b32_e32 v221, v245
	v_mov_b32_e32 v194, v248
	v_mov_b32_e32 v195, v249
	global_load_dwordx4 v[128:131], v[220:221], off
	global_load_dwordx4 v[132:135], v[220:221], off offset:256
	s_mov_b32 s2, 0x8000
	v_lshl_add_u64 v[220:221], v[244:245], 0, s[2:3]
	s_mov_b32 s2, 0x26000
	v_lshl_add_u64 v[196:197], v[248:249], 0, s[2:3]
	global_load_dwordx4 v[136:139], v[220:221], off
	global_load_dwordx4 v[140:143], v[220:221], off offset:256
	s_mov_b32 s2, 0x10000
	v_lshl_add_u64 v[220:221], v[244:245], 0, s[2:3]
	s_mov_b32 s2, 0x4c000
	v_lshl_add_u64 v[208:209], v[248:249], 0, s[2:3]
	global_load_dwordx4 v[144:147], v[220:221], off
	global_load_dwordx4 v[148:151], v[220:221], off offset:256
	s_mov_b32 s2, 0x18000
	v_lshl_add_u64 v[220:221], v[244:245], 0, s[2:3]
	s_mov_b32 s2, 0x72000
	v_lshl_add_u64 v[210:211], v[248:249], 0, s[2:3]
	global_load_dwordx4 v[152:155], v[220:221], off
	global_load_dwordx4 v[156:159], v[220:221], off offset:256
	s_and_b64 vcc, exec, s[6:7]
	s_cbranch_vccz .Llean_E_nop0
	global_load_dwordx4 v[160:163], v[194:195], off
	global_load_dwordx4 v[164:167], v[194:195], off offset:256
	global_load_dwordx4 v[168:171], v[196:197], off
	global_load_dwordx4 v[172:175], v[196:197], off offset:256
	global_load_dwordx4 v[176:179], v[208:209], off
	global_load_dwordx4 v[180:183], v[208:209], off offset:256
	global_load_dwordx4 v[184:187], v[210:211], off
	global_load_dwordx4 v[188:191], v[210:211], off offset:256
.Llean_E_nop0:
	s_waitcnt vmcnt(0)
	v_lshlrev_b32_e32 v224, 16, v128
	v_and_b32_e32 v225, 0xffff0000, v128
	v_lshlrev_b32_e32 v226, 16, v129
	v_and_b32_e32 v227, 0xffff0000, v129
	v_lshlrev_b32_e32 v228, 16, v130
	v_and_b32_e32 v229, 0xffff0000, v130
	v_lshlrev_b32_e32 v230, 16, v131
	v_and_b32_e32 v231, 0xffff0000, v131
	v_lshlrev_b32_e32 v232, 16, v160
	v_and_b32_e32 v233, 0xffff0000, v160
	v_lshlrev_b32_e32 v234, 16, v161
	v_and_b32_e32 v235, 0xffff0000, v161
	v_lshlrev_b32_e32 v236, 16, v162
	v_and_b32_e32 v237, 0xffff0000, v162
	v_lshlrev_b32_e32 v238, 16, v163
	v_and_b32_e32 v239, 0xffff0000, v163
	v_fma_f32 v124, v124, v224, v232
	v_fma_f32 v125, v125, v225, v233
	v_fma_f32 v126, v126, v226, v234
	v_fma_f32 v127, v127, v227, v235
	v_fma_f32 v120, v120, v228, v236
	v_fma_f32 v121, v121, v229, v237
	v_fma_f32 v122, v122, v230, v238
	v_fma_f32 v123, v123, v231, v239
	v_cvt_pk_bf16_f32 v124, v124, v125
	v_cvt_pk_bf16_f32 v125, v126, v127
	v_cvt_pk_bf16_f32 v126, v120, v121
	v_cvt_pk_bf16_f32 v127, v122, v123
	v_lshlrev_b32_e32 v224, 16, v132
	v_and_b32_e32 v225, 0xffff0000, v132
	v_lshlrev_b32_e32 v226, 16, v133
	v_and_b32_e32 v227, 0xffff0000, v133
	v_lshlrev_b32_e32 v228, 16, v134
	v_and_b32_e32 v229, 0xffff0000, v134
	v_lshlrev_b32_e32 v230, 16, v135
	v_and_b32_e32 v231, 0xffff0000, v135
	v_lshlrev_b32_e32 v232, 16, v164
	v_and_b32_e32 v233, 0xffff0000, v164
	v_lshlrev_b32_e32 v234, 16, v165
	v_and_b32_e32 v235, 0xffff0000, v165
	v_lshlrev_b32_e32 v236, 16, v166
	v_and_b32_e32 v237, 0xffff0000, v166
	v_lshlrev_b32_e32 v238, 16, v167
	v_and_b32_e32 v239, 0xffff0000, v167
	v_fma_f32 v116, v116, v224, v232
	v_fma_f32 v117, v117, v225, v233
	v_fma_f32 v118, v118, v226, v234
	v_fma_f32 v119, v119, v227, v235
	v_fma_f32 v108, v108, v228, v236
	v_fma_f32 v109, v109, v229, v237
	v_fma_f32 v110, v110, v230, v238
	v_fma_f32 v111, v111, v231, v239
	v_cvt_pk_bf16_f32 v116, v116, v117
	v_cvt_pk_bf16_f32 v117, v118, v119
	v_cvt_pk_bf16_f32 v118, v108, v109
	v_cvt_pk_bf16_f32 v119, v110, v111
	v_lshlrev_b32_e32 v224, 16, v136
	v_and_b32_e32 v225, 0xffff0000, v136
	v_lshlrev_b32_e32 v226, 16, v137
	v_and_b32_e32 v227, 0xffff0000, v137
	v_lshlrev_b32_e32 v228, 16, v138
	v_and_b32_e32 v229, 0xffff0000, v138
	v_lshlrev_b32_e32 v230, 16, v139
	v_and_b32_e32 v231, 0xffff0000, v139
	v_lshlrev_b32_e32 v232, 16, v168
	v_and_b32_e32 v233, 0xffff0000, v168
	v_lshlrev_b32_e32 v234, 16, v169
	v_and_b32_e32 v235, 0xffff0000, v169
	v_lshlrev_b32_e32 v236, 16, v170
	v_and_b32_e32 v237, 0xffff0000, v170
	v_lshlrev_b32_e32 v238, 16, v171
	v_and_b32_e32 v239, 0xffff0000, v171
	v_fma_f32 v112, v112, v224, v232
	v_fma_f32 v113, v113, v225, v233
	v_fma_f32 v114, v114, v226, v234
	v_fma_f32 v115, v115, v227, v235
; __device__ __forceinline__ unsigned cvt_pk_bf16(float lo, float hi) { unsigned r; asm volatile("v_cvt_pk_bf16_f32 %0, %1, %2" : "=v"(r) : "v"(lo), "v"(hi)); return r; }
; #define GAS __attribute__((address_space(1)))
; DI float bf_lo(unsigned w) { return __uint_as_float(w << 16); }
; DI float bf_hi(unsigned w) { return __uint_as_float(w & 0xffff0000u); }
;     DI void operator()(AccRef acc, const pg8::Unit& u, int wr, int wc, int, int) const {
;     ...
;                     const int lrow = u.pm * 256 + ai * 128 + wr * 64 + m * 16 + fr, col = u.pn * 256 + bj * 128 + wc * 32 + 8 * fq;
;                     gq[m][bj] = *(const GAS u32x4*)(G + (size_t)lrow * DM + col);
;                     pq[m][bj] = (u32x4){0u, 0u, 0u, 0u};
;                     if (has_prev) pq[m][bj] = *(const GAS u32x4*)(Mo + (size_t)lrow * ZW + col);
;                 }
;             asm volatile("" ::: "memory");
; #pragma unroll
;             for (int m = 0; m < 4; ++m) {
;                 const int lrow = u.pm * 256 + ai * 128 + wr * 64 + m * 16 + fr;
;                 EPI_COLS_BEGIN
;                     const size_t off = (size_t)lrow * ZW + col;
;                     const u32x4 g = gq[m][bj], p = pq[m][bj];
;                     v0[0] = v0[0] * bf_lo(g.x) + bf_lo(p.x); v0[1] = v0[1] * bf_hi(g.x) + bf_hi(p.x); v0[2] = v0[2] * bf_lo(g.y) + bf_lo(p.y); v0[3] = v0[3] * bf_hi(g.y) + bf_hi(p.y);
;                     v1[0] = v1[0] * bf_lo(g.z) + bf_lo(p.z); v1[1] = v1[1] * bf_hi(g.z) + bf_hi(p.z); v1[2] = v1[2] * bf_lo(g.w) + bf_lo(p.w); v1[3] = v1[3] * bf_hi(g.w) + bf_hi(p.w);
;                     u32x4 w; w.x = cvt_pk_bf16(v0[0], v0[1]); w.y = cvt_pk_bf16(v0[2], v0[3]); w.z = cvt_pk_bf16(v1[0], v1[1]); w.w = cvt_pk_bf16(v1[2], v1[3]);
;                     *(GAS u32x4*)(dummy ? dummy + lane_ * 8 : Mo + off) = w;
	v_fma_f32 v104, v104, v228, v236
	v_fma_f32 v105, v105, v229, v237
	v_fma_f32 v106, v106, v230, v238
	v_fma_f32 v107, v107, v231, v239
	v_cvt_pk_bf16_f32 v112, v112, v113
	v_cvt_pk_bf16_f32 v113, v114, v115
	v_cvt_pk_bf16_f32 v114, v104, v105
	v_cvt_pk_bf16_f32 v115, v106, v107
	v_lshlrev_b32_e32 v224, 16, v140
	v_and_b32_e32 v225, 0xffff0000, v140
	v_lshlrev_b32_e32 v226, 16, v141
	v_and_b32_e32 v227, 0xffff0000, v141
	v_lshlrev_b32_e32 v228, 16, v142
	v_and_b32_e32 v229, 0xffff0000, v142
	v_lshlrev_b32_e32 v230, 16, v143
	v_and_b32_e32 v231, 0xffff0000, v143
	v_lshlrev_b32_e32 v232, 16, v172
	v_and_b32_e32 v233, 0xffff0000, v172
	v_lshlrev_b32_e32 v234, 16, v173
	v_and_b32_e32 v235, 0xffff0000, v173
	v_lshlrev_b32_e32 v236, 16, v174
	v_and_b32_e32 v237, 0xffff0000, v174
	v_lshlrev_b32_e32 v238, 16, v175
	v_and_b32_e32 v239, 0xffff0000, v175
	v_fma_f32 v100, v100, v224, v232
	v_fma_f32 v101, v101, v225, v233
	v_fma_f32 v102, v102, v226, v234
	v_fma_f32 v103, v103, v227, v235
	v_fma_f32 v92, v92, v228, v236
	v_fma_f32 v93, v93, v229, v237
	v_fma_f32 v94, v94, v230, v238
	v_fma_f32 v95, v95, v231, v239
	v_cvt_pk_bf16_f32 v100, v100, v101
	v_cvt_pk_bf16_f32 v101, v102, v103
	v_cvt_pk_bf16_f32 v102, v92, v93
	v_cvt_pk_bf16_f32 v103, v94, v95
	v_lshlrev_b32_e32 v224, 16, v144
	v_and_b32_e32 v225, 0xffff0000, v144
	v_lshlrev_b32_e32 v226, 16, v145
	v_and_b32_e32 v227, 0xffff0000, v145
	v_lshlrev_b32_e32 v228, 16, v146
	v_and_b32_e32 v229, 0xffff0000, v146
	v_lshlrev_b32_e32 v230, 16, v147
	v_and_b32_e32 v231, 0xffff0000, v147
	v_lshlrev_b32_e32 v232, 16, v176
	v_and_b32_e32 v233, 0xffff0000, v176
	v_lshlrev_b32_e32 v234, 16, v177
	v_and_b32_e32 v235, 0xffff0000, v177
	v_lshlrev_b32_e32 v236, 16, v178
	v_and_b32_e32 v237, 0xffff0000, v178
	v_lshlrev_b32_e32 v238, 16, v179
	v_and_b32_e32 v239, 0xffff0000, v179
	v_fma_f32 v96, v96, v224, v232
	v_fma_f32 v97, v97, v225, v233
	v_fma_f32 v98, v98, v226, v234
	v_fma_f32 v99, v99, v227, v235
	v_fma_f32 v88, v88, v228, v236
	v_fma_f32 v89, v89, v229, v237
	v_fma_f32 v90, v90, v230, v238
	v_fma_f32 v91, v91, v231, v239
	v_cvt_pk_bf16_f32 v96, v96, v97
	v_cvt_pk_bf16_f32 v97, v98, v99
	v_cvt_pk_bf16_f32 v98, v88, v89
	v_cvt_pk_bf16_f32 v99, v90, v91
	v_lshlrev_b32_e32 v224, 16, v148
	v_and_b32_e32 v225, 0xffff0000, v148
	v_lshlrev_b32_e32 v226, 16, v149
	v_and_b32_e32 v227, 0xffff0000, v149
	v_lshlrev_b32_e32 v228, 16, v150
	v_and_b32_e32 v229, 0xffff0000, v150
	v_lshlrev_b32_e32 v230, 16, v151
	v_and_b32_e32 v231, 0xffff0000, v151
	v_lshlrev_b32_e32 v232, 16, v180
	v_and_b32_e32 v233, 0xffff0000, v180
	v_lshlrev_b32_e32 v234, 16, v181
	v_and_b32_e32 v235, 0xffff0000, v181
	v_lshlrev_b32_e32 v236, 16, v182
	v_and_b32_e32 v237, 0xffff0000, v182
	v_lshlrev_b32_e32 v238, 16, v183
	v_and_b32_e32 v239, 0xffff0000, v183
	v_fma_f32 v84, v84, v224, v232
	v_fma_f32 v85, v85, v225, v233
	v_fma_f32 v86, v86, v226, v234
	v_fma_f32 v87, v87, v227, v235
	v_fma_f32 v76, v76, v228, v236
	v_fma_f32 v77, v77, v229, v237
	v_fma_f32 v78, v78, v230, v238
	v_fma_f32 v79, v79, v231, v239
	v_cvt_pk_bf16_f32 v84, v84, v85
	v_cvt_pk_bf16_f32 v85, v86, v87
	v_cvt_pk_bf16_f32 v86, v76, v77
	v_cvt_pk_bf16_f32 v87, v78, v79
	v_lshlrev_b32_e32 v224, 16, v152
	v_and_b32_e32 v225, 0xffff0000, v152
	v_lshlrev_b32_e32 v226, 16, v153
	v_and_b32_e32 v227, 0xffff0000, v153
	v_lshlrev_b32_e32 v228, 16, v154
	v_and_b32_e32 v229, 0xffff0000, v154
	v_lshlrev_b32_e32 v230, 16, v155
	v_and_b32_e32 v231, 0xffff0000, v155
	v_lshlrev_b32_e32 v232, 16, v184
	v_and_b32_e32 v233, 0xffff0000, v184
	v_lshlrev_b32_e32 v234, 16, v185
	v_and_b32_e32 v235, 0xffff0000, v185
	v_lshlrev_b32_e32 v236, 16, v186
	v_and_b32_e32 v237, 0xffff0000, v186
	v_lshlrev_b32_e32 v238, 16, v187
	v_and_b32_e32 v239, 0xffff0000, v187
	v_fma_f32 v80, v80, v224, v232
	v_fma_f32 v81, v81, v225, v233
	v_fma_f32 v82, v82, v226, v234
	v_fma_f32 v83, v83, v227, v235
	v_fma_f32 v72, v72, v228, v236
	v_fma_f32 v73, v73, v229, v237
	v_fma_f32 v74, v74, v230, v238
	v_fma_f32 v75, v75, v231, v239
	v_cvt_pk_bf16_f32 v80, v80, v81
	v_cvt_pk_bf16_f32 v81, v82, v83
	v_cvt_pk_bf16_f32 v82, v72, v73
	v_cvt_pk_bf16_f32 v83, v74, v75
	v_lshlrev_b32_e32 v224, 16, v156
	v_and_b32_e32 v225, 0xffff0000, v156
	v_lshlrev_b32_e32 v226, 16, v157
	v_and_b32_e32 v227, 0xffff0000, v157
	v_lshlrev_b32_e32 v228, 16, v158
	v_and_b32_e32 v229, 0xffff0000, v158
	v_lshlrev_b32_e32 v230, 16, v159
	v_and_b32_e32 v231, 0xffff0000, v159
	v_lshlrev_b32_e32 v232, 16, v188
	v_and_b32_e32 v233, 0xffff0000, v188
	v_lshlrev_b32_e32 v234, 16, v189
	v_and_b32_e32 v235, 0xffff0000, v189
	v_lshlrev_b32_e32 v236, 16, v190
	v_and_b32_e32 v237, 0xffff0000, v190
	v_lshlrev_b32_e32 v238, 16, v191
	v_and_b32_e32 v239, 0xffff0000, v191
	v_fma_f32 v68, v68, v224, v232
	v_fma_f32 v69, v69, v225, v233
	v_fma_f32 v70, v70, v226, v234
	v_fma_f32 v71, v71, v227, v235
	v_fma_f32 v64, v64, v228, v236
	v_fma_f32 v65, v65, v229, v237
	v_fma_f32 v66, v66, v230, v238
	v_fma_f32 v67, v67, v231, v239
	v_cvt_pk_bf16_f32 v68, v68, v69
	v_cvt_pk_bf16_f32 v69, v70, v71
	v_cvt_pk_bf16_f32 v70, v64, v65
	v_cvt_pk_bf16_f32 v71, v66, v67
	s_mov_b32 s2, 0x40000
	v_lshl_add_u64 v[220:221], v[244:245], 0, s[2:3]
	s_mov_b32 s2, 0x130000
	v_lshl_add_u64 v[212:213], v[248:249], 0, s[2:3]
	global_load_dwordx4 v[128:131], v[220:221], off
	global_load_dwordx4 v[132:135], v[220:221], off offset:256
	s_mov_b32 s2, 0x48000
	v_lshl_add_u64 v[220:221], v[244:245], 0, s[2:3]
	s_mov_b32 s2, 0x156000
	v_lshl_add_u64 v[214:215], v[248:249], 0, s[2:3]
	global_load_dwordx4 v[136:139], v[220:221], off
	global_load_dwordx4 v[140:143], v[220:221], off offset:256
	s_mov_b32 s2, 0x50000
	v_lshl_add_u64 v[220:221], v[244:245], 0, s[2:3]
	s_mov_b32 s2, 0x17c000
	v_lshl_add_u64 v[216:217], v[248:249], 0, s[2:3]
	global_load_dwordx4 v[144:147], v[220:221], off
	global_load_dwordx4 v[148:151], v[220:221], off offset:256
	s_mov_b32 s2, 0x58000
	v_lshl_add_u64 v[220:221], v[244:245], 0, s[2:3]
	s_mov_b32 s2, 0x1a2000
	v_lshl_add_u64 v[218:219], v[248:249], 0, s[2:3]
	global_load_dwordx4 v[152:155], v[220:221], off
	global_load_dwordx4 v[156:159], v[220:221], off offset:256
	s_and_b64 vcc, exec, s[6:7]
	s_cbranch_vccz .Llean_E_nop1
	global_load_dwordx4 v[160:163], v[212:213], off
	global_load_dwordx4 v[164:167], v[212:213], off offset:256
	global_load_dwordx4 v[168:171], v[214:215], off
	global_load_dwordx4 v[172:175], v[214:215], off offset:256
	global_load_dwordx4 v[176:179], v[216:217], off
	global_load_dwordx4 v[180:183], v[216:217], off offset:256
	global_load_dwordx4 v[184:187], v[218:219], off
	global_load_dwordx4 v[188:191], v[218:219], off offset:256
; __device__ __forceinline__ unsigned cvt_pk_bf16(float lo, float hi) { unsigned r; asm volatile("v_cvt_pk_bf16_f32 %0, %1, %2" : "=v"(r) : "v"(lo), "v"(hi)); return r; }
; #define GAS __attribute__((address_space(1)))
; DI float bf_lo(unsigned w) { return __uint_as_float(w << 16); }
; DI float bf_hi(unsigned w) { return __uint_as_float(w & 0xffff0000u); }
;     DI void operator()(AccRef acc, const pg8::Unit& u, int wr, int wc, int, int) const {
;     ...
;             for (int m = 0; m < 4; ++m) {
;                 const int lrow = u.pm * 256 + ai * 128 + wr * 64 + m * 16 + fr;
;                 EPI_COLS_BEGIN
;                     const size_t off = (size_t)lrow * ZW + col;
;                     const u32x4 g = gq[m][bj], p = pq[m][bj];
;                     v0[0] = v0[0] * bf_lo(g.x) + bf_lo(p.x); v0[1] = v0[1] * bf_hi(g.x) + bf_hi(p.x); v0[2] = v0[2] * bf_lo(g.y) + bf_lo(p.y); v0[3] = v0[3] * bf_hi(g.y) + bf_hi(p.y);
;                     v1[0] = v1[0] * bf_lo(g.z) + bf_lo(p.z); v1[1] = v1[1] * bf_hi(g.z) + bf_hi(p.z); v1[2] = v1[2] * bf_lo(g.w) + bf_lo(p.w); v1[3] = v1[3] * bf_hi(g.w) + bf_hi(p.w);
;                     u32x4 w; w.x = cvt_pk_bf16(v0[0], v0[1]); w.y = cvt_pk_bf16(v0[2], v0[3]); w.z = cvt_pk_bf16(v1[0], v1[1]); w.w = cvt_pk_bf16(v1[2], v1[3]);
;                     *(GAS u32x4*)(dummy ? dummy + lane_ * 8 : Mo + off) = w;
.Llean_E_nop1:
	global_store_dwordx4 v[194:195], v[124:127], off
	global_store_dwordx4 v[194:195], v[116:119], off offset:256
	global_store_dwordx4 v[196:197], v[112:115], off
	global_store_dwordx4 v[196:197], v[100:103], off offset:256
	global_store_dwordx4 v[208:209], v[96:99], off
	global_store_dwordx4 v[208:209], v[84:87], off offset:256
	global_store_dwordx4 v[210:211], v[80:83], off
	global_store_dwordx4 v[210:211], v[68:71], off offset:256
	s_waitcnt vmcnt(8)
	v_lshlrev_b32_e32 v224, 16, v128
	v_and_b32_e32 v225, 0xffff0000, v128
	v_lshlrev_b32_e32 v226, 16, v129
	v_and_b32_e32 v227, 0xffff0000, v129
	v_lshlrev_b32_e32 v228, 16, v130
	v_and_b32_e32 v229, 0xffff0000, v130
	v_lshlrev_b32_e32 v230, 16, v131
	v_and_b32_e32 v231, 0xffff0000, v131
	v_lshlrev_b32_e32 v232, 16, v160
	v_and_b32_e32 v233, 0xffff0000, v160
	v_lshlrev_b32_e32 v234, 16, v161
	v_and_b32_e32 v235, 0xffff0000, v161
	v_lshlrev_b32_e32 v236, 16, v162
	v_and_b32_e32 v237, 0xffff0000, v162
	v_lshlrev_b32_e32 v238, 16, v163
	v_and_b32_e32 v239, 0xffff0000, v163
	v_fma_f32 v60, v60, v224, v232
	v_fma_f32 v61, v61, v225, v233
	v_fma_f32 v62, v62, v226, v234
	v_fma_f32 v63, v63, v227, v235
	v_fma_f32 v56, v56, v228, v236
	v_fma_f32 v57, v57, v229, v237
	v_fma_f32 v58, v58, v230, v238
	v_fma_f32 v59, v59, v231, v239
	v_cvt_pk_bf16_f32 v60, v60, v61
	v_cvt_pk_bf16_f32 v61, v62, v63
	v_cvt_pk_bf16_f32 v62, v56, v57
	v_cvt_pk_bf16_f32 v63, v58, v59
	v_lshlrev_b32_e32 v224, 16, v132
	v_and_b32_e32 v225, 0xffff0000, v132
	v_lshlrev_b32_e32 v226, 16, v133
	v_and_b32_e32 v227, 0xffff0000, v133
	v_lshlrev_b32_e32 v228, 16, v134
	v_and_b32_e32 v229, 0xffff0000, v134
	v_lshlrev_b32_e32 v230, 16, v135
	v_and_b32_e32 v231, 0xffff0000, v135
	v_lshlrev_b32_e32 v232, 16, v164
	v_and_b32_e32 v233, 0xffff0000, v164
	v_lshlrev_b32_e32 v234, 16, v165
	v_and_b32_e32 v235, 0xffff0000, v165
	v_lshlrev_b32_e32 v236, 16, v166
	v_and_b32_e32 v237, 0xffff0000, v166
	v_lshlrev_b32_e32 v238, 16, v167
	v_and_b32_e32 v239, 0xffff0000, v167
	v_fma_f32 v52, v52, v224, v232
	v_fma_f32 v53, v53, v225, v233
	v_fma_f32 v54, v54, v226, v234
	v_fma_f32 v55, v55, v227, v235
	v_fma_f32 v44, v44, v228, v236
	v_fma_f32 v45, v45, v229, v237
	v_fma_f32 v46, v46, v230, v238
	v_fma_f32 v47, v47, v231, v239
	v_cvt_pk_bf16_f32 v52, v52, v53
	v_cvt_pk_bf16_f32 v53, v54, v55
	v_cvt_pk_bf16_f32 v54, v44, v45
	v_cvt_pk_bf16_f32 v55, v46, v47
	v_lshlrev_b32_e32 v224, 16, v136
	v_and_b32_e32 v225, 0xffff0000, v136
	v_lshlrev_b32_e32 v226, 16, v137
	v_and_b32_e32 v227, 0xffff0000, v137
	v_lshlrev_b32_e32 v228, 16, v138
	v_and_b32_e32 v229, 0xffff0000, v138
	v_lshlrev_b32_e32 v230, 16, v139
	v_and_b32_e32 v231, 0xffff0000, v139
	v_lshlrev_b32_e32 v232, 16, v168
	v_and_b32_e32 v233, 0xffff0000, v168
	v_lshlrev_b32_e32 v234, 16, v169
	v_and_b32_e32 v235, 0xffff0000, v169
	v_lshlrev_b32_e32 v236, 16, v170
	v_and_b32_e32 v237, 0xffff0000, v170
	v_lshlrev_b32_e32 v238, 16, v171
	v_and_b32_e32 v239, 0xffff0000, v171
	v_fma_f32 v48, v48, v224, v232
	v_fma_f32 v49, v49, v225, v233
	v_fma_f32 v50, v50, v226, v234
	v_fma_f32 v51, v51, v227, v235
	v_fma_f32 v40, v40, v228, v236
	v_fma_f32 v41, v41, v229, v237
	v_fma_f32 v42, v42, v230, v238
	v_fma_f32 v43, v43, v231, v239
	v_cvt_pk_bf16_f32 v48, v48, v49
	v_cvt_pk_bf16_f32 v49, v50, v51
	v_cvt_pk_bf16_f32 v50, v40, v41
	v_cvt_pk_bf16_f32 v51, v42, v43
	v_lshlrev_b32_e32 v224, 16, v140
	v_and_b32_e32 v225, 0xffff0000, v140
	v_lshlrev_b32_e32 v226, 16, v141
	v_and_b32_e32 v227, 0xffff0000, v141
	v_lshlrev_b32_e32 v228, 16, v142
	v_and_b32_e32 v229, 0xffff0000, v142
	v_lshlrev_b32_e32 v230, 16, v143
	v_and_b32_e32 v231, 0xffff0000, v143
	v_lshlrev_b32_e32 v232, 16, v172
	v_and_b32_e32 v233, 0xffff0000, v172
	v_lshlrev_b32_e32 v234, 16, v173
	v_and_b32_e32 v235, 0xffff0000, v173
	v_lshlrev_b32_e32 v236, 16, v174
	v_and_b32_e32 v237, 0xffff0000, v174
	v_lshlrev_b32_e32 v238, 16, v175
	v_and_b32_e32 v239, 0xffff0000, v175
	v_fma_f32 v36, v36, v224, v232
	v_fma_f32 v37, v37, v225, v233
	v_fma_f32 v38, v38, v226, v234
	v_fma_f32 v39, v39, v227, v235
	v_fma_f32 v28, v28, v228, v236
	v_fma_f32 v29, v29, v229, v237
	v_fma_f32 v30, v30, v230, v238
	v_fma_f32 v31, v31, v231, v239
	v_cvt_pk_bf16_f32 v36, v36, v37
	v_cvt_pk_bf16_f32 v37, v38, v39
	v_cvt_pk_bf16_f32 v38, v28, v29
	v_cvt_pk_bf16_f32 v39, v30, v31
	v_lshlrev_b32_e32 v224, 16, v144
; __device__ __forceinline__ unsigned cvt_pk_bf16(float lo, float hi) { unsigned r; asm volatile("v_cvt_pk_bf16_f32 %0, %1, %2" : "=v"(r) : "v"(lo), "v"(hi)); return r; }
; #define GAS __attribute__((address_space(1)))
; DI float bf_lo(unsigned w) { return __uint_as_float(w << 16); }
; DI float bf_hi(unsigned w) { return __uint_as_float(w & 0xffff0000u); }
;     DI void operator()(AccRef acc, const pg8::Unit& u, int wr, int wc, int, int) const {
;     ...
;             for (int m = 0; m < 4; ++m) {
;                 const int lrow = u.pm * 256 + ai * 128 + wr * 64 + m * 16 + fr;
;                 EPI_COLS_BEGIN
;                     const size_t off = (size_t)lrow * ZW + col;
;                     const u32x4 g = gq[m][bj], p = pq[m][bj];
;                     v0[0] = v0[0] * bf_lo(g.x) + bf_lo(p.x); v0[1] = v0[1] * bf_hi(g.x) + bf_hi(p.x); v0[2] = v0[2] * bf_lo(g.y) + bf_lo(p.y); v0[3] = v0[3] * bf_hi(g.y) + bf_hi(p.y);
;                     v1[0] = v1[0] * bf_lo(g.z) + bf_lo(p.z); v1[1] = v1[1] * bf_hi(g.z) + bf_hi(p.z); v1[2] = v1[2] * bf_lo(g.w) + bf_lo(p.w); v1[3] = v1[3] * bf_hi(g.w) + bf_hi(p.w);
;                     u32x4 w; w.x = cvt_pk_bf16(v0[0], v0[1]); w.y = cvt_pk_bf16(v0[2], v0[3]); w.z = cvt_pk_bf16(v1[0], v1[1]); w.w = cvt_pk_bf16(v1[2], v1[3]);
;                     *(GAS u32x4*)(dummy ? dummy + lane_ * 8 : Mo + off) = w;
	v_and_b32_e32 v225, 0xffff0000, v144
	v_lshlrev_b32_e32 v226, 16, v145
	v_and_b32_e32 v227, 0xffff0000, v145
	v_lshlrev_b32_e32 v228, 16, v146
	v_and_b32_e32 v229, 0xffff0000, v146
	v_lshlrev_b32_e32 v230, 16, v147
	v_and_b32_e32 v231, 0xffff0000, v147
	v_lshlrev_b32_e32 v232, 16, v176
	v_and_b32_e32 v233, 0xffff0000, v176
	v_lshlrev_b32_e32 v234, 16, v177
	v_and_b32_e32 v235, 0xffff0000, v177
	v_lshlrev_b32_e32 v236, 16, v178
	v_and_b32_e32 v237, 0xffff0000, v178
	v_lshlrev_b32_e32 v238, 16, v179
	v_and_b32_e32 v239, 0xffff0000, v179
	v_fma_f32 v32, v32, v224, v232
	v_fma_f32 v33, v33, v225, v233
	v_fma_f32 v34, v34, v226, v234
	v_fma_f32 v35, v35, v227, v235
	v_fma_f32 v24, v24, v228, v236
	v_fma_f32 v25, v25, v229, v237
	v_fma_f32 v26, v26, v230, v238
	v_fma_f32 v27, v27, v231, v239
	v_cvt_pk_bf16_f32 v32, v32, v33
	v_cvt_pk_bf16_f32 v33, v34, v35
	v_cvt_pk_bf16_f32 v34, v24, v25
	v_cvt_pk_bf16_f32 v35, v26, v27
	v_lshlrev_b32_e32 v224, 16, v148
	v_and_b32_e32 v225, 0xffff0000, v148
	v_lshlrev_b32_e32 v226, 16, v149
	v_and_b32_e32 v227, 0xffff0000, v149
	v_lshlrev_b32_e32 v228, 16, v150
	v_and_b32_e32 v229, 0xffff0000, v150
	v_lshlrev_b32_e32 v230, 16, v151
	v_and_b32_e32 v231, 0xffff0000, v151
	v_lshlrev_b32_e32 v232, 16, v180
	v_and_b32_e32 v233, 0xffff0000, v180
	v_lshlrev_b32_e32 v234, 16, v181
	v_and_b32_e32 v235, 0xffff0000, v181
	v_lshlrev_b32_e32 v236, 16, v182
	v_and_b32_e32 v237, 0xffff0000, v182
	v_lshlrev_b32_e32 v238, 16, v183
	v_and_b32_e32 v239, 0xffff0000, v183
	v_fma_f32 v20, v20, v224, v232
	v_fma_f32 v21, v21, v225, v233
	v_fma_f32 v22, v22, v226, v234
	v_fma_f32 v23, v23, v227, v235
	v_fma_f32 v12, v12, v228, v236
	v_fma_f32 v13, v13, v229, v237
	v_fma_f32 v14, v14, v230, v238
	v_fma_f32 v15, v15, v231, v239
	v_cvt_pk_bf16_f32 v20, v20, v21
	v_cvt_pk_bf16_f32 v21, v22, v23
	v_cvt_pk_bf16_f32 v22, v12, v13
	v_cvt_pk_bf16_f32 v23, v14, v15
	v_lshlrev_b32_e32 v224, 16, v152
	v_and_b32_e32 v225, 0xffff0000, v152
	v_lshlrev_b32_e32 v226, 16, v153
	v_and_b32_e32 v227, 0xffff0000, v153
	v_lshlrev_b32_e32 v228, 16, v154
	v_and_b32_e32 v229, 0xffff0000, v154
	v_lshlrev_b32_e32 v230, 16, v155
	v_and_b32_e32 v231, 0xffff0000, v155
	v_lshlrev_b32_e32 v232, 16, v184
	v_and_b32_e32 v233, 0xffff0000, v184
	v_lshlrev_b32_e32 v234, 16, v185
	v_and_b32_e32 v235, 0xffff0000, v185
	v_lshlrev_b32_e32 v236, 16, v186
	v_and_b32_e32 v237, 0xffff0000, v186
	v_lshlrev_b32_e32 v238, 16, v187
	v_and_b32_e32 v239, 0xffff0000, v187
	v_fma_f32 v16, v16, v224, v232
	v_fma_f32 v17, v17, v225, v233
	v_fma_f32 v18, v18, v226, v234
	v_fma_f32 v19, v19, v227, v235
	v_fma_f32 v8, v8, v228, v236
	v_fma_f32 v9, v9, v229, v237
	v_fma_f32 v10, v10, v230, v238
	v_fma_f32 v11, v11, v231, v239
	v_cvt_pk_bf16_f32 v16, v16, v17
	v_cvt_pk_bf16_f32 v17, v18, v19
	v_cvt_pk_bf16_f32 v18, v8, v9
	v_cvt_pk_bf16_f32 v19, v10, v11
	v_lshlrev_b32_e32 v224, 16, v156
	v_and_b32_e32 v225, 0xffff0000, v156
	v_lshlrev_b32_e32 v226, 16, v157
	v_and_b32_e32 v227, 0xffff0000, v157
	v_lshlrev_b32_e32 v228, 16, v158
	v_and_b32_e32 v229, 0xffff0000, v158
	v_lshlrev_b32_e32 v230, 16, v159
	v_and_b32_e32 v231, 0xffff0000, v159
	v_lshlrev_b32_e32 v232, 16, v188
	v_and_b32_e32 v233, 0xffff0000, v188
	v_lshlrev_b32_e32 v234, 16, v189
	v_and_b32_e32 v235, 0xffff0000, v189
	v_lshlrev_b32_e32 v236, 16, v190
	v_and_b32_e32 v237, 0xffff0000, v190
	v_lshlrev_b32_e32 v238, 16, v191
	v_and_b32_e32 v239, 0xffff0000, v191
	v_fma_f32 v4, v4, v224, v232
	v_fma_f32 v5, v5, v225, v233
	v_fma_f32 v6, v6, v226, v234
	v_fma_f32 v7, v7, v227, v235
	v_fma_f32 v0, v0, v228, v236
	v_fma_f32 v1, v1, v229, v237
	v_fma_f32 v2, v2, v230, v238
	v_fma_f32 v3, v3, v231, v239
	v_cvt_pk_bf16_f32 v4, v4, v5
	v_cvt_pk_bf16_f32 v5, v6, v7
	v_cvt_pk_bf16_f32 v6, v0, v1
	v_cvt_pk_bf16_f32 v7, v2, v3
	global_store_dwordx4 v[212:213], v[60:63], off
	global_store_dwordx4 v[212:213], v[52:55], off offset:256
	global_store_dwordx4 v[214:215], v[48:51], off
	global_store_dwordx4 v[214:215], v[36:39], off offset:256
	global_store_dwordx4 v[216:217], v[32:35], off
	global_store_dwordx4 v[216:217], v[20:23], off offset:256
	global_store_dwordx4 v[218:219], v[16:19], off
	global_store_dwordx4 v[218:219], v[4:7], off offset:256
	s_and_b64 vcc, exec, s[0:1]
	s_cbranch_vccnz .LBB0_754
	s_andn2_b64 vcc, exec, s[10:11]
	s_cbranch_vccnz .LBB0_753
	s_barrier
	s_branch .LBB0_753

; #define GAS __attribute__((address_space(1)))
;     DI void operator()(AccRef acc, const pg8::Unit& u, int wr, int wc, int, int) const {
;     ...
;                     const int lrow = u.pm * 256 + ai * 128 + wr * 64 + m * 16 + fr, col = u.pn * 256 + bj * 128 + wc * 32 + 8 * fq;
;                     gq[m][bj] = *(const GAS u32x4*)(G + (size_t)lrow * DM + col);
;                     pq[m][bj] = (u32x4){0u, 0u, 0u, 0u};
;                     if (has_prev) pq[m][bj] = *(const GAS u32x4*)(Mo + (size_t)lrow * ZW + col);
.LBB0_769:
	s_branch .Llean_E_entry
	s_lshl_b32 s2, s92, 8
	v_mbcnt_lo_u32_b32 v128, -1, 0
	v_mbcnt_hi_u32_b32 v128, -1, v128
	s_add_i32 s2, s2, s84
	v_and_or_b32 v210, v128, 15, s2
	s_lshl_b32 s2, s78, 8
	v_ashrrev_i32_e32 v128, 1, v128
	v_and_b32_e32 v128, -8, v128
	s_or_b32 s2, s2, s85
	v_ashrrev_i32_e32 v211, 31, v210
	v_add_u32_e32 v208, s2, v128
	v_lshlrev_b64 v[128:129], 11, v[210:211]
	v_lshl_add_u64 v[128:129], s[70:71], 0, v[128:129]
	v_ashrrev_i32_e32 v209, 31, v208
	v_lshl_add_u64 v[130:131], v[208:209], 1, v[128:129]
	global_load_dwordx4 v[184:187], v[130:131], off
	v_mov_b64_e32 v[128:129], s[68:69]
	v_mad_i64_i32 v[218:219], s[2:3], v210, s51, v[128:129]
	v_cndmask_b32_e64 v128, 0, 1, s[6:7]
	v_mov_b32_e32 v168, 0
	v_cmp_ne_u32_e64 s[4:5], 1, v128
	s_andn2_b64 vcc, exec, s[6:7]
	v_lshl_add_u64 v[128:129], v[208:209], 1, v[218:219]
	v_mov_b32_e32 v188, 0
	v_mov_b32_e32 v189, 0
	v_mov_b32_e32 v190, 0
	v_mov_b32_e32 v191, 0
	s_cbranch_vccnz .LBB0_771
	global_load_dwordx4 v[188:191], v[128:129], off

;     DI void operator()(AccRef acc, const pg8::Unit& u, int wr, int wc, int, int) const {
;     ...
;                 { const float rsk = (kind == 4) ? rs * -1.4426950408889634f : rs; v0 = v0 * rsk; v1 = v1 * rsk; }
.Llean_F_entry:
	v_and_b32_e32 v136, 15, v226
	v_lshrrev_b32_e32 v137, 4, v226
	v_or_b32_e32 v136, s49, v136
	v_lshl_add_u32 v138, s6, 8, v136
	v_lshlrev_b32_e32 v140, 4, v137
	v_lshl_add_u32 v140, v138, 6, v140
	v_add_u32_e32 v140, 0x2000, v140
	v_mov_b32_e32 v141, 0
	v_lshl_add_u64 v[144:145], s[26:27], 0, v[140:141]
	global_load_dwordx4 v[72:75], v[144:145], off
	global_load_dwordx4 v[76:79], v[144:145], off offset:1024
	global_load_dwordx4 v[80:83], v[144:145], off offset:2048
	global_load_dwordx4 v[84:87], v[144:145], off offset:3072
	v_mul_lo_u32 v146, v138, s39
	v_mov_b32_e32 v147, 0
	s_lshl_b32 s0, s14, 8
	s_add_i32 s0, s0, s20
	v_lshl_add_u32 v148, v137, 3, s0
	v_lshlrev_b32_e32 v148, 1, v148
	v_mov_b32_e32 v149, 0
	v_lshl_add_u64 v[146:147], v[146:147], 1, s[72:73]
	v_lshl_add_u64 v[146:147], v[146:147], 0, v[148:149]
	s_lshl_b32 s2, s39, 5
	s_mov_b32 s3, 0
	s_mul_i32 s0, s39, 0xa0
	s_mov_b32 s1, 0
	v_mov_b32_e32 v213, 0x260
	v_add_f32_e32 v168, v194, v195
	v_add_f32_e32 v169, v196, v197
	v_add_f32_e32 v168, v168, v169
	v_add_f32_e32 v170, v228, v229
	v_add_f32_e32 v171, v230, v231
	v_add_f32_e32 v170, v170, v171
	v_add_f32_e32 v172, v232, v233
	v_add_f32_e32 v173, v234, v235
	v_add_f32_e32 v172, v172, v173
	v_add_f32_e32 v174, v236, v237
	v_add_f32_e32 v175, v238, v239
	v_add_f32_e32 v174, v174, v175
	ds_swizzle_b32 v169, v168 offset:swizzle(SWAP,16)
	ds_swizzle_b32 v171, v170 offset:swizzle(SWAP,16)
	ds_swizzle_b32 v173, v172 offset:swizzle(SWAP,16)
	ds_swizzle_b32 v175, v174 offset:swizzle(SWAP,16)
	s_waitcnt lgkmcnt(0)
	v_add_f32_e32 v168, v168, v169
	v_add_f32_e32 v170, v170, v171
	v_add_f32_e32 v172, v172, v173
	v_add_f32_e32 v174, v174, v175
	v_mov_b32_e32 v169, v168
	v_mov_b32_e32 v171, v170
	v_mov_b32_e32 v173, v172
	v_mov_b32_e32 v175, v174
	s_nop 1
	v_permlane32_swap_b32_e32 v168, v169
	v_permlane32_swap_b32_e32 v170, v171
	v_permlane32_swap_b32_e32 v172, v173
	v_permlane32_swap_b32_e32 v174, v175
	v_add_f32_e32 v168, v168, v169
	v_add_f32_e32 v170, v170, v171
	v_add_f32_e32 v172, v172, v173
	v_add_f32_e32 v174, v174, v175
	v_fmamk_f32 v168, v168, 0x3a800000, v246
	v_fmamk_f32 v170, v170, 0x3a800000, v246
	v_sqrt_f32_e32 v208, v168
	v_sqrt_f32_e32 v214, v170
	v_add_u32_e32 v209, -1, v208
	v_add_u32_e32 v215, -1, v214
	v_fma_f32 v210, -v209, v208, v168
	v_fma_f32 v216, -v215, v214, v170
	v_cmp_ge_f32_e64 s[98:99], 0, v210
	v_cmp_ge_f32_e64 s[16:17], 0, v216
	v_add_u32_e32 v210, 1, v208
	v_add_u32_e32 v216, 1, v214
	v_cndmask_b32_e64 v209, v208, v209, s[98:99]
	v_cndmask_b32_e64 v215, v214, v215, s[16:17]
	v_fma_f32 v211, -v210, v208, v168
	v_fma_f32 v217, -v216, v214, v170
	v_cmp_lt_f32_e64 s[98:99], 0, v211
	v_cmp_lt_f32_e64 s[16:17], 0, v217
	s_nop 0
	v_cndmask_b32_e64 v208, v209, v210, s[98:99]
	v_cndmask_b32_e64 v214, v215, v216, s[16:17]
	v_rcp_f32_e32 v209, v208
	v_rcp_f32_e32 v215, v214
	v_fma_f32 v210, -v208, v209, 1.0
	v_fma_f32 v216, -v214, v215, 1.0
	v_fmac_f32_e32 v209, v210, v209
	v_fmac_f32_e32 v215, v216, v215
	v_fma_f32 v212, -v208, v209, 1.0
	v_fma_f32 v218, -v214, v215, 1.0
	v_fma_f32 v211, v212, v209, v209
	v_fma_f32 v217, v218, v215, v215
	v_fma_f32 v212, -v208, v211, 1.0
	v_fma_f32 v218, -v214, v217, 1.0
	v_fma_f32 v168, v212, v209, v211
	v_fma_f32 v170, v218, v215, v217
	v_fmamk_f32 v172, v172, 0x3a800000, v246
	v_fmamk_f32 v174, v174, 0x3a800000, v246
	v_sqrt_f32_e32 v208, v172
	v_sqrt_f32_e32 v214, v174
	v_add_u32_e32 v209, -1, v208
	v_add_u32_e32 v215, -1, v214
	v_fma_f32 v210, -v209, v208, v172
	v_fma_f32 v216, -v215, v214, v174
	v_cmp_ge_f32_e64 s[98:99], 0, v210
	v_cmp_ge_f32_e64 s[16:17], 0, v216
	v_add_u32_e32 v210, 1, v208
	v_add_u32_e32 v216, 1, v214
	v_cndmask_b32_e64 v209, v208, v209, s[98:99]
	v_cndmask_b32_e64 v215, v214, v215, s[16:17]
	v_fma_f32 v211, -v210, v208, v172
	v_fma_f32 v217, -v216, v214, v174
	v_cmp_lt_f32_e64 s[98:99], 0, v211
	v_cmp_lt_f32_e64 s[16:17], 0, v217
	s_nop 0
	v_cndmask_b32_e64 v208, v209, v210, s[98:99]
	v_cndmask_b32_e64 v214, v215, v216, s[16:17]
	v_rcp_f32_e32 v209, v208
	v_rcp_f32_e32 v215, v214
	v_fma_f32 v210, -v208, v209, 1.0
	v_fma_f32 v216, -v214, v215, 1.0
	v_fmac_f32_e32 v209, v210, v209
	v_fmac_f32_e32 v215, v216, v215
	v_fma_f32 v212, -v208, v209, 1.0
	v_fma_f32 v218, -v214, v215, 1.0
	v_fma_f32 v211, v212, v209, v209
	v_fma_f32 v217, v218, v215, v215
	v_fma_f32 v212, -v208, v211, 1.0
	v_fma_f32 v218, -v214, v217, 1.0
	v_fma_f32 v172, v212, v209, v211
	v_fma_f32 v174, v218, v215, v217
	s_cmp_eq_u32 s8, 4
	s_cbranch_scc1 .Llean_F_sig
; __device__ __forceinline__ unsigned cvt_pk_bf16(float lo, float hi) { unsigned r; asm volatile("v_cvt_pk_bf16_f32 %0, %1, %2" : "=v"(r) : "v"(lo), "v"(hi)); return r; }
; #define GAS __attribute__((address_space(1)))
;     DI void operator()(AccRef acc, const pg8::Unit& u, int wr, int wc, int, int) const {
;     ...
;                 { const float rsk = (kind == 4) ? rs * -1.4426950408889634f : rs; v0 = v0 * rsk; v1 = v1 * rsk; }
;     ...
;                 u32x4 w; w.x = cvt_pk_bf16(v0[0], v0[1]); w.y = cvt_pk_bf16(v0[2], v0[3]); w.z = cvt_pk_bf16(v1[0], v1[1]); w.w = cvt_pk_bf16(v1[2], v1[3]);
;                 *(GAS u32x4*)(dummy ? dummy + lane_ * 8 : Z + (size_t)lrow * ldz + col) = w;
	v_pk_mul_f32 v[188:189], v[188:189], v[168:169] op_sel_hi:[1,0]
	v_pk_mul_f32 v[190:191], v[190:191], v[168:169] op_sel_hi:[1,0]
	v_pk_mul_f32 v[184:185], v[184:185], v[168:169] op_sel_hi:[1,0]
	v_pk_mul_f32 v[186:187], v[186:187], v[168:169] op_sel_hi:[1,0]
	v_cvt_pk_bf16_f32 v104, v188, v189
	v_cvt_pk_bf16_f32 v105, v190, v191
	v_cvt_pk_bf16_f32 v106, v184, v185
	v_cvt_pk_bf16_f32 v107, v186, v187
	global_store_dwordx4 v[146:147], v[104:107], off
	v_pk_mul_f32 v[164:165], v[164:165], v[168:169] op_sel_hi:[1,0]
	v_pk_mul_f32 v[166:167], v[166:167], v[168:169] op_sel_hi:[1,0]
	v_pk_mul_f32 v[160:161], v[160:161], v[168:169] op_sel_hi:[1,0]
	v_pk_mul_f32 v[162:163], v[162:163], v[168:169] op_sel_hi:[1,0]
	v_cvt_pk_bf16_f32 v108, v164, v165
	v_cvt_pk_bf16_f32 v109, v166, v167
	v_cvt_pk_bf16_f32 v110, v160, v161
	v_cvt_pk_bf16_f32 v111, v162, v163
	global_store_dwordx4 v[146:147], v[108:111], off offset:256
	v_lshl_add_u64 v[150:151], v[146:147], 0, s[2:3]
	v_pk_mul_f32 v[156:157], v[156:157], v[170:171] op_sel_hi:[1,0]
	v_pk_mul_f32 v[158:159], v[158:159], v[170:171] op_sel_hi:[1,0]
	v_pk_mul_f32 v[152:153], v[152:153], v[170:171] op_sel_hi:[1,0]
	v_pk_mul_f32 v[154:155], v[154:155], v[170:171] op_sel_hi:[1,0]
	v_cvt_pk_bf16_f32 v112, v156, v157
	v_cvt_pk_bf16_f32 v113, v158, v159
	v_cvt_pk_bf16_f32 v114, v152, v153
	v_cvt_pk_bf16_f32 v115, v154, v155
	global_store_dwordx4 v[150:151], v[112:115], off
	v_pk_mul_f32 v[132:133], v[132:133], v[170:171] op_sel_hi:[1,0]
	v_pk_mul_f32 v[134:135], v[134:135], v[170:171] op_sel_hi:[1,0]
	v_pk_mul_f32 v[128:129], v[128:129], v[170:171] op_sel_hi:[1,0]
	v_pk_mul_f32 v[130:131], v[130:131], v[170:171] op_sel_hi:[1,0]
	v_cvt_pk_bf16_f32 v116, v132, v133
	v_cvt_pk_bf16_f32 v117, v134, v135
	v_cvt_pk_bf16_f32 v118, v128, v129
	v_cvt_pk_bf16_f32 v119, v130, v131
	global_store_dwordx4 v[150:151], v[116:119], off offset:256
	v_lshl_add_u64 v[146:147], v[150:151], 0, s[2:3]
	v_pk_mul_f32 v[124:125], v[124:125], v[172:173] op_sel_hi:[1,0]
	v_pk_mul_f32 v[126:127], v[126:127], v[172:173] op_sel_hi:[1,0]
	v_pk_mul_f32 v[120:121], v[120:121], v[172:173] op_sel_hi:[1,0]
	v_pk_mul_f32 v[122:123], v[122:123], v[172:173] op_sel_hi:[1,0]
	v_cvt_pk_bf16_f32 v104, v124, v125
	v_cvt_pk_bf16_f32 v105, v126, v127
	v_cvt_pk_bf16_f32 v106, v120, v121
	v_cvt_pk_bf16_f32 v107, v122, v123
	global_store_dwordx4 v[146:147], v[104:107], off
	v_pk_mul_f32 v[100:101], v[100:101], v[172:173] op_sel_hi:[1,0]
	v_pk_mul_f32 v[102:103], v[102:103], v[172:173] op_sel_hi:[1,0]
	v_pk_mul_f32 v[96:97], v[96:97], v[172:173] op_sel_hi:[1,0]
	v_pk_mul_f32 v[98:99], v[98:99], v[172:173] op_sel_hi:[1,0]
	v_cvt_pk_bf16_f32 v108, v100, v101
	v_cvt_pk_bf16_f32 v109, v102, v103
	v_cvt_pk_bf16_f32 v110, v96, v97
	v_cvt_pk_bf16_f32 v111, v98, v99
	global_store_dwordx4 v[146:147], v[108:111], off offset:256
	v_lshl_add_u64 v[150:151], v[146:147], 0, s[2:3]
	v_pk_mul_f32 v[92:93], v[92:93], v[174:175] op_sel_hi:[1,0]
	v_pk_mul_f32 v[94:95], v[94:95], v[174:175] op_sel_hi:[1,0]
	v_pk_mul_f32 v[88:89], v[88:89], v[174:175] op_sel_hi:[1,0]
	v_pk_mul_f32 v[90:91], v[90:91], v[174:175] op_sel_hi:[1,0]
	v_cvt_pk_bf16_f32 v112, v92, v93
	v_cvt_pk_bf16_f32 v113, v94, v95
	v_cvt_pk_bf16_f32 v114, v88, v89
	v_cvt_pk_bf16_f32 v115, v90, v91
	global_store_dwordx4 v[150:151], v[112:115], off
	v_pk_mul_f32 v[68:69], v[68:69], v[174:175] op_sel_hi:[1,0]
	v_pk_mul_f32 v[70:71], v[70:71], v[174:175] op_sel_hi:[1,0]
	v_pk_mul_f32 v[64:65], v[64:65], v[174:175] op_sel_hi:[1,0]
	v_pk_mul_f32 v[66:67], v[66:67], v[174:175] op_sel_hi:[1,0]
	v_cvt_pk_bf16_f32 v116, v68, v69
	v_cvt_pk_bf16_f32 v117, v70, v71
	v_cvt_pk_bf16_f32 v118, v64, v65
	v_cvt_pk_bf16_f32 v119, v66, v67
	global_store_dwordx4 v[150:151], v[116:119], off offset:256
	v_lshl_add_u64 v[146:147], v[150:151], 0, s[0:1]
	s_waitcnt vmcnt(8)
	v_add_f32_e32 v176, v72, v73
	v_add_f32_e32 v177, v74, v75
	v_add_f32_e32 v176, v176, v177
	v_add_f32_e32 v178, v76, v77
	v_add_f32_e32 v179, v78, v79
	v_add_f32_e32 v178, v178, v179
	v_add_f32_e32 v180, v80, v81
	v_add_f32_e32 v181, v82, v83
	v_add_f32_e32 v180, v180, v181
	v_add_f32_e32 v182, v84, v85
	v_add_f32_e32 v183, v86, v87
	v_add_f32_e32 v182, v182, v183
	ds_swizzle_b32 v177, v176 offset:swizzle(SWAP,16)
	ds_swizzle_b32 v179, v178 offset:swizzle(SWAP,16)
	ds_swizzle_b32 v181, v180 offset:swizzle(SWAP,16)
	ds_swizzle_b32 v183, v182 offset:swizzle(SWAP,16)
	s_waitcnt lgkmcnt(0)
; __device__ __forceinline__ unsigned cvt_pk_bf16(float lo, float hi) { unsigned r; asm volatile("v_cvt_pk_bf16_f32 %0, %1, %2" : "=v"(r) : "v"(lo), "v"(hi)); return r; }
; #define GAS __attribute__((address_space(1)))
;     DI void operator()(AccRef acc, const pg8::Unit& u, int wr, int wc, int, int) const {
;     ...
;                 { const float rsk = (kind == 4) ? rs * -1.4426950408889634f : rs; v0 = v0 * rsk; v1 = v1 * rsk; }
;     ...
;                 u32x4 w; w.x = cvt_pk_bf16(v0[0], v0[1]); w.y = cvt_pk_bf16(v0[2], v0[3]); w.z = cvt_pk_bf16(v1[0], v1[1]); w.w = cvt_pk_bf16(v1[2], v1[3]);
;                 *(GAS u32x4*)(dummy ? dummy + lane_ * 8 : Z + (size_t)lrow * ldz + col) = w;
	v_add_f32_e32 v176, v176, v177
	v_add_f32_e32 v178, v178, v179
	v_add_f32_e32 v180, v180, v181
	v_add_f32_e32 v182, v182, v183
	v_mov_b32_e32 v177, v176
	v_mov_b32_e32 v179, v178
	v_mov_b32_e32 v181, v180
	v_mov_b32_e32 v183, v182
	s_nop 1
	v_permlane32_swap_b32_e32 v176, v177
	v_permlane32_swap_b32_e32 v178, v179
	v_permlane32_swap_b32_e32 v180, v181
	v_permlane32_swap_b32_e32 v182, v183
	v_add_f32_e32 v176, v176, v177
	v_add_f32_e32 v178, v178, v179
	v_add_f32_e32 v180, v180, v181
	v_add_f32_e32 v182, v182, v183
	v_fmamk_f32 v176, v176, 0x3a800000, v246
	v_fmamk_f32 v178, v178, 0x3a800000, v246
	v_sqrt_f32_e32 v208, v176
	v_sqrt_f32_e32 v214, v178
	v_add_u32_e32 v209, -1, v208
	v_add_u32_e32 v215, -1, v214
	v_fma_f32 v210, -v209, v208, v176
	v_fma_f32 v216, -v215, v214, v178
	v_cmp_ge_f32_e64 s[98:99], 0, v210
	v_cmp_ge_f32_e64 s[16:17], 0, v216
	v_add_u32_e32 v210, 1, v208
	v_add_u32_e32 v216, 1, v214
	v_cndmask_b32_e64 v209, v208, v209, s[98:99]
	v_cndmask_b32_e64 v215, v214, v215, s[16:17]
	v_fma_f32 v211, -v210, v208, v176
	v_fma_f32 v217, -v216, v214, v178
	v_cmp_lt_f32_e64 s[98:99], 0, v211
	v_cmp_lt_f32_e64 s[16:17], 0, v217
	s_nop 0
	v_cndmask_b32_e64 v208, v209, v210, s[98:99]
	v_cndmask_b32_e64 v214, v215, v216, s[16:17]
	v_rcp_f32_e32 v209, v208
	v_rcp_f32_e32 v215, v214
	v_fma_f32 v210, -v208, v209, 1.0
	v_fma_f32 v216, -v214, v215, 1.0
	v_fmac_f32_e32 v209, v210, v209
	v_fmac_f32_e32 v215, v216, v215
	v_fma_f32 v212, -v208, v209, 1.0
	v_fma_f32 v218, -v214, v215, 1.0
	v_fma_f32 v211, v212, v209, v209
	v_fma_f32 v217, v218, v215, v215
	v_fma_f32 v212, -v208, v211, 1.0
	v_fma_f32 v218, -v214, v217, 1.0
	v_fma_f32 v176, v212, v209, v211
	v_fma_f32 v178, v218, v215, v217
	v_fmamk_f32 v180, v180, 0x3a800000, v246
	v_fmamk_f32 v182, v182, 0x3a800000, v246
	v_sqrt_f32_e32 v208, v180
	v_sqrt_f32_e32 v214, v182
	v_add_u32_e32 v209, -1, v208
	v_add_u32_e32 v215, -1, v214
	v_fma_f32 v210, -v209, v208, v180
	v_fma_f32 v216, -v215, v214, v182
	v_cmp_ge_f32_e64 s[98:99], 0, v210
	v_cmp_ge_f32_e64 s[16:17], 0, v216
	v_add_u32_e32 v210, 1, v208
	v_add_u32_e32 v216, 1, v214
	v_cndmask_b32_e64 v209, v208, v209, s[98:99]
	v_cndmask_b32_e64 v215, v214, v215, s[16:17]
	v_fma_f32 v211, -v210, v208, v180
	v_fma_f32 v217, -v216, v214, v182
	v_cmp_lt_f32_e64 s[98:99], 0, v211
	v_cmp_lt_f32_e64 s[16:17], 0, v217
	s_nop 0
	v_cndmask_b32_e64 v208, v209, v210, s[98:99]
	v_cndmask_b32_e64 v214, v215, v216, s[16:17]
	v_rcp_f32_e32 v209, v208
	v_rcp_f32_e32 v215, v214
	v_fma_f32 v210, -v208, v209, 1.0
	v_fma_f32 v216, -v214, v215, 1.0
	v_fmac_f32_e32 v209, v210, v209
	v_fmac_f32_e32 v215, v216, v215
	v_fma_f32 v212, -v208, v209, 1.0
	v_fma_f32 v218, -v214, v215, 1.0
	v_fma_f32 v211, v212, v209, v209
	v_fma_f32 v217, v218, v215, v215
	v_fma_f32 v212, -v208, v211, 1.0
	v_fma_f32 v218, -v214, v217, 1.0
	v_fma_f32 v180, v212, v209, v211
	v_fma_f32 v182, v218, v215, v217
	v_pk_mul_f32 v[60:61], v[60:61], v[176:177] op_sel_hi:[1,0]
	v_pk_mul_f32 v[62:63], v[62:63], v[176:177] op_sel_hi:[1,0]
	v_pk_mul_f32 v[56:57], v[56:57], v[176:177] op_sel_hi:[1,0]
	v_pk_mul_f32 v[58:59], v[58:59], v[176:177] op_sel_hi:[1,0]
	v_cvt_pk_bf16_f32 v104, v60, v61
	v_cvt_pk_bf16_f32 v105, v62, v63
	v_cvt_pk_bf16_f32 v106, v56, v57
	v_cvt_pk_bf16_f32 v107, v58, v59
	global_store_dwordx4 v[146:147], v[104:107], off
	v_pk_mul_f32 v[52:53], v[52:53], v[176:177] op_sel_hi:[1,0]
	v_pk_mul_f32 v[54:55], v[54:55], v[176:177] op_sel_hi:[1,0]
	v_pk_mul_f32 v[48:49], v[48:49], v[176:177] op_sel_hi:[1,0]
	v_pk_mul_f32 v[50:51], v[50:51], v[176:177] op_sel_hi:[1,0]
	v_cvt_pk_bf16_f32 v108, v52, v53
	v_cvt_pk_bf16_f32 v109, v54, v55
	v_cvt_pk_bf16_f32 v110, v48, v49
	v_cvt_pk_bf16_f32 v111, v50, v51
	global_store_dwordx4 v[146:147], v[108:111], off offset:256
	v_lshl_add_u64 v[150:151], v[146:147], 0, s[2:3]
	v_pk_mul_f32 v[44:45], v[44:45], v[178:179] op_sel_hi:[1,0]
	v_pk_mul_f32 v[46:47], v[46:47], v[178:179] op_sel_hi:[1,0]
	v_pk_mul_f32 v[40:41], v[40:41], v[178:179] op_sel_hi:[1,0]
	v_pk_mul_f32 v[42:43], v[42:43], v[178:179] op_sel_hi:[1,0]
	v_cvt_pk_bf16_f32 v112, v44, v45
	v_cvt_pk_bf16_f32 v113, v46, v47
	v_cvt_pk_bf16_f32 v114, v40, v41
	v_cvt_pk_bf16_f32 v115, v42, v43
	global_store_dwordx4 v[150:151], v[112:115], off
	v_pk_mul_f32 v[36:37], v[36:37], v[178:179] op_sel_hi:[1,0]
	v_pk_mul_f32 v[38:39], v[38:39], v[178:179] op_sel_hi:[1,0]
	v_pk_mul_f32 v[32:33], v[32:33], v[178:179] op_sel_hi:[1,0]
	v_pk_mul_f32 v[34:35], v[34:35], v[178:179] op_sel_hi:[1,0]
	v_cvt_pk_bf16_f32 v116, v36, v37
	v_cvt_pk_bf16_f32 v117, v38, v39
	v_cvt_pk_bf16_f32 v118, v32, v33
	v_cvt_pk_bf16_f32 v119, v34, v35
	global_store_dwordx4 v[150:151], v[116:119], off offset:256
	v_lshl_add_u64 v[146:147], v[150:151], 0, s[2:3]
	v_pk_mul_f32 v[28:29], v[28:29], v[180:181] op_sel_hi:[1,0]
	v_pk_mul_f32 v[30:31], v[30:31], v[180:181] op_sel_hi:[1,0]
	v_pk_mul_f32 v[24:25], v[24:25], v[180:181] op_sel_hi:[1,0]
	v_pk_mul_f32 v[26:27], v[26:27], v[180:181] op_sel_hi:[1,0]
	v_cvt_pk_bf16_f32 v104, v28, v29
	v_cvt_pk_bf16_f32 v105, v30, v31
	v_cvt_pk_bf16_f32 v106, v24, v25
	v_cvt_pk_bf16_f32 v107, v26, v27
	global_store_dwordx4 v[146:147], v[104:107], off
	v_pk_mul_f32 v[20:21], v[20:21], v[180:181] op_sel_hi:[1,0]
	v_pk_mul_f32 v[22:23], v[22:23], v[180:181] op_sel_hi:[1,0]
	v_pk_mul_f32 v[16:17], v[16:17], v[180:181] op_sel_hi:[1,0]
	v_pk_mul_f32 v[18:19], v[18:19], v[180:181] op_sel_hi:[1,0]
	v_cvt_pk_bf16_f32 v108, v20, v21
	v_cvt_pk_bf16_f32 v109, v22, v23
	v_cvt_pk_bf16_f32 v110, v16, v17
	v_cvt_pk_bf16_f32 v111, v18, v19
	global_store_dwordx4 v[146:147], v[108:111], off offset:256
	v_lshl_add_u64 v[150:151], v[146:147], 0, s[2:3]
	v_pk_mul_f32 v[12:13], v[12:13], v[182:183] op_sel_hi:[1,0]
	v_pk_mul_f32 v[14:15], v[14:15], v[182:183] op_sel_hi:[1,0]
	v_pk_mul_f32 v[8:9], v[8:9], v[182:183] op_sel_hi:[1,0]
	v_pk_mul_f32 v[10:11], v[10:11], v[182:183] op_sel_hi:[1,0]
	v_cvt_pk_bf16_f32 v112, v12, v13
	v_cvt_pk_bf16_f32 v113, v14, v15
	v_cvt_pk_bf16_f32 v114, v8, v9
	v_cvt_pk_bf16_f32 v115, v10, v11
	global_store_dwordx4 v[150:151], v[112:115], off
	v_pk_mul_f32 v[4:5], v[4:5], v[182:183] op_sel_hi:[1,0]
	v_pk_mul_f32 v[6:7], v[6:7], v[182:183] op_sel_hi:[1,0]
	v_pk_mul_f32 v[0:1], v[0:1], v[182:183] op_sel_hi:[1,0]
	v_pk_mul_f32 v[2:3], v[2:3], v[182:183] op_sel_hi:[1,0]
	v_cvt_pk_bf16_f32 v116, v4, v5
	v_cvt_pk_bf16_f32 v117, v6, v7
	v_cvt_pk_bf16_f32 v118, v0, v1
	v_cvt_pk_bf16_f32 v119, v2, v3
	global_store_dwordx4 v[150:151], v[116:119], off offset:256
	s_branch .Llean_F_exit
; __device__ __forceinline__ unsigned cvt_pk_bf16(float lo, float hi) { unsigned r; asm volatile("v_cvt_pk_bf16_f32 %0, %1, %2" : "=v"(r) : "v"(lo), "v"(hi)); return r; }
; #define GAS __attribute__((address_space(1)))
;     DI void operator()(AccRef acc, const pg8::Unit& u, int wr, int wc, int, int) const {
;     ...
;                 } else if (kind == 4) {
; #pragma unroll
;                     for (int e = 0; e < 4; ++e) { v0[e] = __builtin_amdgcn_rcpf(1.0f + __builtin_amdgcn_exp2f(v0[e])); v1[e] = __builtin_amdgcn_rcpf(1.0f + __builtin_amdgcn_exp2f(v1[e])); }
;                 }
;                 u32x4 w; w.x = cvt_pk_bf16(v0[0], v0[1]); w.y = cvt_pk_bf16(v0[2], v0[3]); w.z = cvt_pk_bf16(v1[0], v1[1]); w.w = cvt_pk_bf16(v1[2], v1[3]);
;                 *(GAS u32x4*)(dummy ? dummy + lane_ * 8 : Z + (size_t)lrow * ldz + col) = w;
.Llean_F_sig:
	v_mul_f32_e32 v168, 0xbfb8aa3b, v168
	v_mul_f32_e32 v170, 0xbfb8aa3b, v170
	v_mul_f32_e32 v172, 0xbfb8aa3b, v172
	v_mul_f32_e32 v174, 0xbfb8aa3b, v174
	v_pk_mul_f32 v[188:189], v[188:189], v[168:169] op_sel_hi:[1,0]
	v_pk_mul_f32 v[190:191], v[190:191], v[168:169] op_sel_hi:[1,0]
	v_pk_mul_f32 v[184:185], v[184:185], v[168:169] op_sel_hi:[1,0]
	v_pk_mul_f32 v[186:187], v[186:187], v[168:169] op_sel_hi:[1,0]
	v_exp_f32_e32 v188, v188
	v_exp_f32_e32 v189, v189
	v_exp_f32_e32 v190, v190
	v_exp_f32_e32 v191, v191
	v_exp_f32_e32 v184, v184
	v_exp_f32_e32 v185, v185
	v_exp_f32_e32 v186, v186
	v_exp_f32_e32 v187, v187
	v_add_f32_e32 v188, 1.0, v188
	v_add_f32_e32 v189, 1.0, v189
	v_add_f32_e32 v190, 1.0, v190
	v_add_f32_e32 v191, 1.0, v191
	v_add_f32_e32 v184, 1.0, v184
	v_add_f32_e32 v185, 1.0, v185
	v_add_f32_e32 v186, 1.0, v186
	v_add_f32_e32 v187, 1.0, v187
	v_rcp_f32_e32 v188, v188
	v_rcp_f32_e32 v189, v189
	v_rcp_f32_e32 v190, v190
	v_rcp_f32_e32 v191, v191
	v_rcp_f32_e32 v184, v184
	v_rcp_f32_e32 v185, v185
	v_rcp_f32_e32 v186, v186
	v_rcp_f32_e32 v187, v187
	s_nop 0
	v_cvt_pk_bf16_f32 v104, v188, v189
	v_cvt_pk_bf16_f32 v105, v190, v191
	v_cvt_pk_bf16_f32 v106, v184, v185
	v_cvt_pk_bf16_f32 v107, v186, v187
	global_store_dwordx4 v[146:147], v[104:107], off
	v_pk_mul_f32 v[164:165], v[164:165], v[168:169] op_sel_hi:[1,0]
	v_pk_mul_f32 v[166:167], v[166:167], v[168:169] op_sel_hi:[1,0]
	v_pk_mul_f32 v[160:161], v[160:161], v[168:169] op_sel_hi:[1,0]
	v_pk_mul_f32 v[162:163], v[162:163], v[168:169] op_sel_hi:[1,0]
	v_exp_f32_e32 v164, v164
	v_exp_f32_e32 v165, v165
	v_exp_f32_e32 v166, v166
	v_exp_f32_e32 v167, v167
	v_exp_f32_e32 v160, v160
	v_exp_f32_e32 v161, v161
	v_exp_f32_e32 v162, v162
	v_exp_f32_e32 v163, v163
	v_add_f32_e32 v164, 1.0, v164
	v_add_f32_e32 v165, 1.0, v165
	v_add_f32_e32 v166, 1.0, v166
	v_add_f32_e32 v167, 1.0, v167
	v_add_f32_e32 v160, 1.0, v160
	v_add_f32_e32 v161, 1.0, v161
	v_add_f32_e32 v162, 1.0, v162
	v_add_f32_e32 v163, 1.0, v163
	v_rcp_f32_e32 v164, v164
	v_rcp_f32_e32 v165, v165
	v_rcp_f32_e32 v166, v166
	v_rcp_f32_e32 v167, v167
	v_rcp_f32_e32 v160, v160
	v_rcp_f32_e32 v161, v161
	v_rcp_f32_e32 v162, v162
	v_rcp_f32_e32 v163, v163
	s_nop 0
	v_cvt_pk_bf16_f32 v108, v164, v165
	v_cvt_pk_bf16_f32 v109, v166, v167
	v_cvt_pk_bf16_f32 v110, v160, v161
	v_cvt_pk_bf16_f32 v111, v162, v163
	global_store_dwordx4 v[146:147], v[108:111], off offset:256
	v_lshl_add_u64 v[150:151], v[146:147], 0, s[2:3]
	v_pk_mul_f32 v[156:157], v[156:157], v[170:171] op_sel_hi:[1,0]
	v_pk_mul_f32 v[158:159], v[158:159], v[170:171] op_sel_hi:[1,0]
	v_pk_mul_f32 v[152:153], v[152:153], v[170:171] op_sel_hi:[1,0]
	v_pk_mul_f32 v[154:155], v[154:155], v[170:171] op_sel_hi:[1,0]
	v_exp_f32_e32 v156, v156
	v_exp_f32_e32 v157, v157
	v_exp_f32_e32 v158, v158
	v_exp_f32_e32 v159, v159
	v_exp_f32_e32 v152, v152
	v_exp_f32_e32 v153, v153
	v_exp_f32_e32 v154, v154
	v_exp_f32_e32 v155, v155
	v_add_f32_e32 v156, 1.0, v156
	v_add_f32_e32 v157, 1.0, v157
	v_add_f32_e32 v158, 1.0, v158
	v_add_f32_e32 v159, 1.0, v159
	v_add_f32_e32 v152, 1.0, v152
	v_add_f32_e32 v153, 1.0, v153
	v_add_f32_e32 v154, 1.0, v154
	v_add_f32_e32 v155, 1.0, v155
	v_rcp_f32_e32 v156, v156
	v_rcp_f32_e32 v157, v157
	v_rcp_f32_e32 v158, v158
	v_rcp_f32_e32 v159, v159
	v_rcp_f32_e32 v152, v152
	v_rcp_f32_e32 v153, v153
	v_rcp_f32_e32 v154, v154
	v_rcp_f32_e32 v155, v155
	s_nop 0
	v_cvt_pk_bf16_f32 v112, v156, v157
	v_cvt_pk_bf16_f32 v113, v158, v159
	v_cvt_pk_bf16_f32 v114, v152, v153
	v_cvt_pk_bf16_f32 v115, v154, v155
	global_store_dwordx4 v[150:151], v[112:115], off
	v_pk_mul_f32 v[132:133], v[132:133], v[170:171] op_sel_hi:[1,0]
	v_pk_mul_f32 v[134:135], v[134:135], v[170:171] op_sel_hi:[1,0]
	v_pk_mul_f32 v[128:129], v[128:129], v[170:171] op_sel_hi:[1,0]
	v_pk_mul_f32 v[130:131], v[130:131], v[170:171] op_sel_hi:[1,0]
	v_exp_f32_e32 v132, v132
	v_exp_f32_e32 v133, v133
	v_exp_f32_e32 v134, v134
	v_exp_f32_e32 v135, v135
	v_exp_f32_e32 v128, v128
	v_exp_f32_e32 v129, v129
	v_exp_f32_e32 v130, v130
	v_exp_f32_e32 v131, v131
	v_add_f32_e32 v132, 1.0, v132
	v_add_f32_e32 v133, 1.0, v133
	v_add_f32_e32 v134, 1.0, v134
	v_add_f32_e32 v135, 1.0, v135
	v_add_f32_e32 v128, 1.0, v128
	v_add_f32_e32 v129, 1.0, v129
	v_add_f32_e32 v130, 1.0, v130
	v_add_f32_e32 v131, 1.0, v131
	v_rcp_f32_e32 v132, v132
	v_rcp_f32_e32 v133, v133
	v_rcp_f32_e32 v134, v134
	v_rcp_f32_e32 v135, v135
	v_rcp_f32_e32 v128, v128
	v_rcp_f32_e32 v129, v129
	v_rcp_f32_e32 v130, v130
	v_rcp_f32_e32 v131, v131
	s_nop 0
	v_cvt_pk_bf16_f32 v116, v132, v133
	v_cvt_pk_bf16_f32 v117, v134, v135
	v_cvt_pk_bf16_f32 v118, v128, v129
	v_cvt_pk_bf16_f32 v119, v130, v131
	global_store_dwordx4 v[150:151], v[116:119], off offset:256
	v_lshl_add_u64 v[146:147], v[150:151], 0, s[2:3]
	v_pk_mul_f32 v[124:125], v[124:125], v[172:173] op_sel_hi:[1,0]
	v_pk_mul_f32 v[126:127], v[126:127], v[172:173] op_sel_hi:[1,0]
	v_pk_mul_f32 v[120:121], v[120:121], v[172:173] op_sel_hi:[1,0]
	v_pk_mul_f32 v[122:123], v[122:123], v[172:173] op_sel_hi:[1,0]
	v_exp_f32_e32 v124, v124
	v_exp_f32_e32 v125, v125
	v_exp_f32_e32 v126, v126
	v_exp_f32_e32 v127, v127
	v_exp_f32_e32 v120, v120
	v_exp_f32_e32 v121, v121
	v_exp_f32_e32 v122, v122
	v_exp_f32_e32 v123, v123
	v_add_f32_e32 v124, 1.0, v124
	v_add_f32_e32 v125, 1.0, v125
	v_add_f32_e32 v126, 1.0, v126
	v_add_f32_e32 v127, 1.0, v127
	v_add_f32_e32 v120, 1.0, v120
	v_add_f32_e32 v121, 1.0, v121
	v_add_f32_e32 v122, 1.0, v122
	v_add_f32_e32 v123, 1.0, v123
	v_rcp_f32_e32 v124, v124
	v_rcp_f32_e32 v125, v125
	v_rcp_f32_e32 v126, v126
	v_rcp_f32_e32 v127, v127
	v_rcp_f32_e32 v120, v120
; __device__ __forceinline__ unsigned cvt_pk_bf16(float lo, float hi) { unsigned r; asm volatile("v_cvt_pk_bf16_f32 %0, %1, %2" : "=v"(r) : "v"(lo), "v"(hi)); return r; }
; #define GAS __attribute__((address_space(1)))
;     DI void operator()(AccRef acc, const pg8::Unit& u, int wr, int wc, int, int) const {
;     ...
;                 { const float rsk = (kind == 4) ? rs * -1.4426950408889634f : rs; v0 = v0 * rsk; v1 = v1 * rsk; }
;                 if (kind < 2) {
;                     if (rot) {
;                         f32x4 p0, p1;
; #pragma unroll
;                         for (int e = 0; e < 4; ++e) { p0[e] = lane_xor<16>(v0[e]); p1[e] = lane_xor<16>(v1[e]); }
;                         if (fq == 0) { v0 = v0 * c0 - p0 * s0; v1 = v1 * c1 - p1 * s1; }
;                         else if (fq == 1) { v0 = v0 * c0 + p0 * s0; v1 = v1 * c1 + p1 * s1; }
;                     }
;                     v0 = v0 * qs; v1 = v1 * qs;
;                 } else if (kind == 3) {
;                     f32x2 a = pg8::gelu_pk((f32x2){v0[0], v0[1]}), b = pg8::gelu_pk((f32x2){v0[2], v0[3]}), c = pg8::gelu_pk((f32x2){v1[0], v1[1]}), d = pg8::gelu_pk((f32x2){v1[2], v1[3]});
;                     v0 = (f32x4){a.x, a.y, b.x, b.y}; v1 = (f32x4){c.x, c.y, d.x, d.y};
;                 } else if (kind == 4) {
; #pragma unroll
;                     for (int e = 0; e < 4; ++e) { v0[e] = __builtin_amdgcn_rcpf(1.0f + __builtin_amdgcn_exp2f(v0[e])); v1[e] = __builtin_amdgcn_rcpf(1.0f + __builtin_amdgcn_exp2f(v1[e])); }
;                 }
;                 u32x4 w; w.x = cvt_pk_bf16(v0[0], v0[1]); w.y = cvt_pk_bf16(v0[2], v0[3]); w.z = cvt_pk_bf16(v1[0], v1[1]); w.w = cvt_pk_bf16(v1[2], v1[3]);
;                 *(GAS u32x4*)(dummy ? dummy + lane_ * 8 : Z + (size_t)lrow * ldz + col) = w;
	v_rcp_f32_e32 v121, v121
	v_rcp_f32_e32 v122, v122
	v_rcp_f32_e32 v123, v123
	s_nop 0
	v_cvt_pk_bf16_f32 v104, v124, v125
	v_cvt_pk_bf16_f32 v105, v126, v127
	v_cvt_pk_bf16_f32 v106, v120, v121
	v_cvt_pk_bf16_f32 v107, v122, v123
	global_store_dwordx4 v[146:147], v[104:107], off
	v_pk_mul_f32 v[100:101], v[100:101], v[172:173] op_sel_hi:[1,0]
	v_pk_mul_f32 v[102:103], v[102:103], v[172:173] op_sel_hi:[1,0]
	v_pk_mul_f32 v[96:97], v[96:97], v[172:173] op_sel_hi:[1,0]
	v_pk_mul_f32 v[98:99], v[98:99], v[172:173] op_sel_hi:[1,0]
	v_exp_f32_e32 v100, v100
	v_exp_f32_e32 v101, v101
	v_exp_f32_e32 v102, v102
	v_exp_f32_e32 v103, v103
	v_exp_f32_e32 v96, v96
	v_exp_f32_e32 v97, v97
	v_exp_f32_e32 v98, v98
	v_exp_f32_e32 v99, v99
	v_add_f32_e32 v100, 1.0, v100
	v_add_f32_e32 v101, 1.0, v101
	v_add_f32_e32 v102, 1.0, v102
	v_add_f32_e32 v103, 1.0, v103
	v_add_f32_e32 v96, 1.0, v96
	v_add_f32_e32 v97, 1.0, v97
	v_add_f32_e32 v98, 1.0, v98
	v_add_f32_e32 v99, 1.0, v99
	v_rcp_f32_e32 v100, v100
	v_rcp_f32_e32 v101, v101
	v_rcp_f32_e32 v102, v102
	v_rcp_f32_e32 v103, v103
	v_rcp_f32_e32 v96, v96
	v_rcp_f32_e32 v97, v97
	v_rcp_f32_e32 v98, v98
	v_rcp_f32_e32 v99, v99
	s_nop 0
	v_cvt_pk_bf16_f32 v108, v100, v101
	v_cvt_pk_bf16_f32 v109, v102, v103
	v_cvt_pk_bf16_f32 v110, v96, v97
	v_cvt_pk_bf16_f32 v111, v98, v99
	global_store_dwordx4 v[146:147], v[108:111], off offset:256
	v_lshl_add_u64 v[150:151], v[146:147], 0, s[2:3]
	v_pk_mul_f32 v[92:93], v[92:93], v[174:175] op_sel_hi:[1,0]
	v_pk_mul_f32 v[94:95], v[94:95], v[174:175] op_sel_hi:[1,0]
	v_pk_mul_f32 v[88:89], v[88:89], v[174:175] op_sel_hi:[1,0]
	v_pk_mul_f32 v[90:91], v[90:91], v[174:175] op_sel_hi:[1,0]
	v_exp_f32_e32 v92, v92
	v_exp_f32_e32 v93, v93
	v_exp_f32_e32 v94, v94
	v_exp_f32_e32 v95, v95
	v_exp_f32_e32 v88, v88
	v_exp_f32_e32 v89, v89
	v_exp_f32_e32 v90, v90
	v_exp_f32_e32 v91, v91
	v_add_f32_e32 v92, 1.0, v92
	v_add_f32_e32 v93, 1.0, v93
	v_add_f32_e32 v94, 1.0, v94
	v_add_f32_e32 v95, 1.0, v95
	v_add_f32_e32 v88, 1.0, v88
	v_add_f32_e32 v89, 1.0, v89
	v_add_f32_e32 v90, 1.0, v90
	v_add_f32_e32 v91, 1.0, v91
	v_rcp_f32_e32 v92, v92
	v_rcp_f32_e32 v93, v93
	v_rcp_f32_e32 v94, v94
	v_rcp_f32_e32 v95, v95
	v_rcp_f32_e32 v88, v88
	v_rcp_f32_e32 v89, v89
	v_rcp_f32_e32 v90, v90
	v_rcp_f32_e32 v91, v91
	s_nop 0
	v_cvt_pk_bf16_f32 v112, v92, v93
	v_cvt_pk_bf16_f32 v113, v94, v95
	v_cvt_pk_bf16_f32 v114, v88, v89
	v_cvt_pk_bf16_f32 v115, v90, v91
	global_store_dwordx4 v[150:151], v[112:115], off
	v_pk_mul_f32 v[68:69], v[68:69], v[174:175] op_sel_hi:[1,0]
	v_pk_mul_f32 v[70:71], v[70:71], v[174:175] op_sel_hi:[1,0]
	v_pk_mul_f32 v[64:65], v[64:65], v[174:175] op_sel_hi:[1,0]
	v_pk_mul_f32 v[66:67], v[66:67], v[174:175] op_sel_hi:[1,0]
	v_exp_f32_e32 v68, v68
	v_exp_f32_e32 v69, v69
	v_exp_f32_e32 v70, v70
	v_exp_f32_e32 v71, v71
	v_exp_f32_e32 v64, v64
	v_exp_f32_e32 v65, v65
	v_exp_f32_e32 v66, v66
	v_exp_f32_e32 v67, v67
	v_add_f32_e32 v68, 1.0, v68
	v_add_f32_e32 v69, 1.0, v69
	v_add_f32_e32 v70, 1.0, v70
	v_add_f32_e32 v71, 1.0, v71
	v_add_f32_e32 v64, 1.0, v64
	v_add_f32_e32 v65, 1.0, v65
	v_add_f32_e32 v66, 1.0, v66
	v_add_f32_e32 v67, 1.0, v67
	v_rcp_f32_e32 v68, v68
	v_rcp_f32_e32 v69, v69
	v_rcp_f32_e32 v70, v70
	v_rcp_f32_e32 v71, v71
	v_rcp_f32_e32 v64, v64
	v_rcp_f32_e32 v65, v65
	v_rcp_f32_e32 v66, v66
	v_rcp_f32_e32 v67, v67
	s_nop 0
	v_cvt_pk_bf16_f32 v116, v68, v69
	v_cvt_pk_bf16_f32 v117, v70, v71
	v_cvt_pk_bf16_f32 v118, v64, v65
	v_cvt_pk_bf16_f32 v119, v66, v67
	global_store_dwordx4 v[150:151], v[116:119], off offset:256
	v_lshl_add_u64 v[146:147], v[150:151], 0, s[0:1]
	s_waitcnt vmcnt(8)
	v_add_f32_e32 v176, v72, v73
	v_add_f32_e32 v177, v74, v75
	v_add_f32_e32 v176, v176, v177
	v_add_f32_e32 v178, v76, v77
	v_add_f32_e32 v179, v78, v79
	v_add_f32_e32 v178, v178, v179
	v_add_f32_e32 v180, v80, v81
	v_add_f32_e32 v181, v82, v83
	v_add_f32_e32 v180, v180, v181
	v_add_f32_e32 v182, v84, v85
	v_add_f32_e32 v183, v86, v87
	v_add_f32_e32 v182, v182, v183
	ds_swizzle_b32 v177, v176 offset:swizzle(SWAP,16)
	ds_swizzle_b32 v179, v178 offset:swizzle(SWAP,16)
	ds_swizzle_b32 v181, v180 offset:swizzle(SWAP,16)
	ds_swizzle_b32 v183, v182 offset:swizzle(SWAP,16)
	s_waitcnt lgkmcnt(0)
	v_add_f32_e32 v176, v176, v177
	v_add_f32_e32 v178, v178, v179
	v_add_f32_e32 v180, v180, v181
	v_add_f32_e32 v182, v182, v183
	v_mov_b32_e32 v177, v176
	v_mov_b32_e32 v179, v178
	v_mov_b32_e32 v181, v180
	v_mov_b32_e32 v183, v182
	s_nop 1
	v_permlane32_swap_b32_e32 v176, v177
	v_permlane32_swap_b32_e32 v178, v179
	v_permlane32_swap_b32_e32 v180, v181
	v_permlane32_swap_b32_e32 v182, v183
	v_add_f32_e32 v176, v176, v177
	v_add_f32_e32 v178, v178, v179
	v_add_f32_e32 v180, v180, v181
	v_add_f32_e32 v182, v182, v183
	v_fmamk_f32 v176, v176, 0x3a800000, v246
	v_fmamk_f32 v178, v178, 0x3a800000, v246
	v_sqrt_f32_e32 v208, v176
	v_sqrt_f32_e32 v214, v178
	v_add_u32_e32 v209, -1, v208
	v_add_u32_e32 v215, -1, v214
	v_fma_f32 v210, -v209, v208, v176
	v_fma_f32 v216, -v215, v214, v178
	v_cmp_ge_f32_e64 s[98:99], 0, v210
	v_cmp_ge_f32_e64 s[16:17], 0, v216
	v_add_u32_e32 v210, 1, v208
	v_add_u32_e32 v216, 1, v214
	v_cndmask_b32_e64 v209, v208, v209, s[98:99]
	v_cndmask_b32_e64 v215, v214, v215, s[16:17]
	v_fma_f32 v211, -v210, v208, v176
	v_fma_f32 v217, -v216, v214, v178
	v_cmp_lt_f32_e64 s[98:99], 0, v211
	v_cmp_lt_f32_e64 s[16:17], 0, v217
	s_nop 0
	v_cndmask_b32_e64 v208, v209, v210, s[98:99]
	v_cndmask_b32_e64 v214, v215, v216, s[16:17]
	v_rcp_f32_e32 v209, v208
	v_rcp_f32_e32 v215, v214
	v_fma_f32 v210, -v208, v209, 1.0
	v_fma_f32 v216, -v214, v215, 1.0
	v_fmac_f32_e32 v209, v210, v209
; __device__ __forceinline__ unsigned cvt_pk_bf16(float lo, float hi) { unsigned r; asm volatile("v_cvt_pk_bf16_f32 %0, %1, %2" : "=v"(r) : "v"(lo), "v"(hi)); return r; }
; #define GAS __attribute__((address_space(1)))
;     DI void operator()(AccRef acc, const pg8::Unit& u, int wr, int wc, int, int) const {
;     ...
;                 { const float rsk = (kind == 4) ? rs * -1.4426950408889634f : rs; v0 = v0 * rsk; v1 = v1 * rsk; }
;                 if (kind < 2) {
;                     if (rot) {
;                         f32x4 p0, p1;
; #pragma unroll
;                         for (int e = 0; e < 4; ++e) { p0[e] = lane_xor<16>(v0[e]); p1[e] = lane_xor<16>(v1[e]); }
;                         if (fq == 0) { v0 = v0 * c0 - p0 * s0; v1 = v1 * c1 - p1 * s1; }
;                         else if (fq == 1) { v0 = v0 * c0 + p0 * s0; v1 = v1 * c1 + p1 * s1; }
;                     }
;                     v0 = v0 * qs; v1 = v1 * qs;
;                 } else if (kind == 3) {
;                     f32x2 a = pg8::gelu_pk((f32x2){v0[0], v0[1]}), b = pg8::gelu_pk((f32x2){v0[2], v0[3]}), c = pg8::gelu_pk((f32x2){v1[0], v1[1]}), d = pg8::gelu_pk((f32x2){v1[2], v1[3]});
;                     v0 = (f32x4){a.x, a.y, b.x, b.y}; v1 = (f32x4){c.x, c.y, d.x, d.y};
;                 } else if (kind == 4) {
; #pragma unroll
;                     for (int e = 0; e < 4; ++e) { v0[e] = __builtin_amdgcn_rcpf(1.0f + __builtin_amdgcn_exp2f(v0[e])); v1[e] = __builtin_amdgcn_rcpf(1.0f + __builtin_amdgcn_exp2f(v1[e])); }
;                 }
;                 u32x4 w; w.x = cvt_pk_bf16(v0[0], v0[1]); w.y = cvt_pk_bf16(v0[2], v0[3]); w.z = cvt_pk_bf16(v1[0], v1[1]); w.w = cvt_pk_bf16(v1[2], v1[3]);
;                 *(GAS u32x4*)(dummy ? dummy + lane_ * 8 : Z + (size_t)lrow * ldz + col) = w;
	v_fmac_f32_e32 v215, v216, v215
	v_fma_f32 v212, -v208, v209, 1.0
	v_fma_f32 v218, -v214, v215, 1.0
	v_fma_f32 v211, v212, v209, v209
	v_fma_f32 v217, v218, v215, v215
	v_fma_f32 v212, -v208, v211, 1.0
	v_fma_f32 v218, -v214, v217, 1.0
	v_fma_f32 v176, v212, v209, v211
	v_fma_f32 v178, v218, v215, v217
	v_fmamk_f32 v180, v180, 0x3a800000, v246
	v_fmamk_f32 v182, v182, 0x3a800000, v246
	v_sqrt_f32_e32 v208, v180
	v_sqrt_f32_e32 v214, v182
	v_add_u32_e32 v209, -1, v208
	v_add_u32_e32 v215, -1, v214
	v_fma_f32 v210, -v209, v208, v180
	v_fma_f32 v216, -v215, v214, v182
	v_cmp_ge_f32_e64 s[98:99], 0, v210
	v_cmp_ge_f32_e64 s[16:17], 0, v216
	v_add_u32_e32 v210, 1, v208
	v_add_u32_e32 v216, 1, v214
	v_cndmask_b32_e64 v209, v208, v209, s[98:99]
	v_cndmask_b32_e64 v215, v214, v215, s[16:17]
	v_fma_f32 v211, -v210, v208, v180
	v_fma_f32 v217, -v216, v214, v182
	v_cmp_lt_f32_e64 s[98:99], 0, v211
	v_cmp_lt_f32_e64 s[16:17], 0, v217
	s_nop 0
	v_cndmask_b32_e64 v208, v209, v210, s[98:99]
	v_cndmask_b32_e64 v214, v215, v216, s[16:17]
	v_rcp_f32_e32 v209, v208
	v_rcp_f32_e32 v215, v214
	v_fma_f32 v210, -v208, v209, 1.0
	v_fma_f32 v216, -v214, v215, 1.0
	v_fmac_f32_e32 v209, v210, v209
	v_fmac_f32_e32 v215, v216, v215
	v_fma_f32 v212, -v208, v209, 1.0
	v_fma_f32 v218, -v214, v215, 1.0
	v_fma_f32 v211, v212, v209, v209
	v_fma_f32 v217, v218, v215, v215
	v_fma_f32 v212, -v208, v211, 1.0
	v_fma_f32 v218, -v214, v217, 1.0
	v_fma_f32 v180, v212, v209, v211
	v_fma_f32 v182, v218, v215, v217
	v_mul_f32_e32 v176, 0xbfb8aa3b, v176
	v_mul_f32_e32 v178, 0xbfb8aa3b, v178
	v_mul_f32_e32 v180, 0xbfb8aa3b, v180
	v_mul_f32_e32 v182, 0xbfb8aa3b, v182
	v_pk_mul_f32 v[60:61], v[60:61], v[176:177] op_sel_hi:[1,0]
	v_pk_mul_f32 v[62:63], v[62:63], v[176:177] op_sel_hi:[1,0]
	v_pk_mul_f32 v[56:57], v[56:57], v[176:177] op_sel_hi:[1,0]
	v_pk_mul_f32 v[58:59], v[58:59], v[176:177] op_sel_hi:[1,0]
	v_exp_f32_e32 v60, v60
	v_exp_f32_e32 v61, v61
	v_exp_f32_e32 v62, v62
	v_exp_f32_e32 v63, v63
	v_exp_f32_e32 v56, v56
	v_exp_f32_e32 v57, v57
	v_exp_f32_e32 v58, v58
	v_exp_f32_e32 v59, v59
	v_add_f32_e32 v60, 1.0, v60
	v_add_f32_e32 v61, 1.0, v61
	v_add_f32_e32 v62, 1.0, v62
	v_add_f32_e32 v63, 1.0, v63
	v_add_f32_e32 v56, 1.0, v56
	v_add_f32_e32 v57, 1.0, v57
	v_add_f32_e32 v58, 1.0, v58
	v_add_f32_e32 v59, 1.0, v59
	v_rcp_f32_e32 v60, v60
	v_rcp_f32_e32 v61, v61
	v_rcp_f32_e32 v62, v62
	v_rcp_f32_e32 v63, v63
	v_rcp_f32_e32 v56, v56
	v_rcp_f32_e32 v57, v57
	v_rcp_f32_e32 v58, v58
	v_rcp_f32_e32 v59, v59
	s_nop 0
	v_cvt_pk_bf16_f32 v104, v60, v61
	v_cvt_pk_bf16_f32 v105, v62, v63
	v_cvt_pk_bf16_f32 v106, v56, v57
	v_cvt_pk_bf16_f32 v107, v58, v59
	global_store_dwordx4 v[146:147], v[104:107], off
	v_pk_mul_f32 v[52:53], v[52:53], v[176:177] op_sel_hi:[1,0]
	v_pk_mul_f32 v[54:55], v[54:55], v[176:177] op_sel_hi:[1,0]
	v_pk_mul_f32 v[48:49], v[48:49], v[176:177] op_sel_hi:[1,0]
	v_pk_mul_f32 v[50:51], v[50:51], v[176:177] op_sel_hi:[1,0]
	v_exp_f32_e32 v52, v52
	v_exp_f32_e32 v53, v53
	v_exp_f32_e32 v54, v54
	v_exp_f32_e32 v55, v55
	v_exp_f32_e32 v48, v48
	v_exp_f32_e32 v49, v49
	v_exp_f32_e32 v50, v50
	v_exp_f32_e32 v51, v51
	v_add_f32_e32 v52, 1.0, v52
	v_add_f32_e32 v53, 1.0, v53
	v_add_f32_e32 v54, 1.0, v54
	v_add_f32_e32 v55, 1.0, v55
	v_add_f32_e32 v48, 1.0, v48
	v_add_f32_e32 v49, 1.0, v49
	v_add_f32_e32 v50, 1.0, v50
	v_add_f32_e32 v51, 1.0, v51
	v_rcp_f32_e32 v52, v52
	v_rcp_f32_e32 v53, v53
	v_rcp_f32_e32 v54, v54
	v_rcp_f32_e32 v55, v55
	v_rcp_f32_e32 v48, v48
	v_rcp_f32_e32 v49, v49
	v_rcp_f32_e32 v50, v50
	v_rcp_f32_e32 v51, v51
	s_nop 0
	v_cvt_pk_bf16_f32 v108, v52, v53
	v_cvt_pk_bf16_f32 v109, v54, v55
	v_cvt_pk_bf16_f32 v110, v48, v49
	v_cvt_pk_bf16_f32 v111, v50, v51
	global_store_dwordx4 v[146:147], v[108:111], off offset:256
	v_lshl_add_u64 v[150:151], v[146:147], 0, s[2:3]
	v_pk_mul_f32 v[44:45], v[44:45], v[178:179] op_sel_hi:[1,0]
	v_pk_mul_f32 v[46:47], v[46:47], v[178:179] op_sel_hi:[1,0]
	v_pk_mul_f32 v[40:41], v[40:41], v[178:179] op_sel_hi:[1,0]
	v_pk_mul_f32 v[42:43], v[42:43], v[178:179] op_sel_hi:[1,0]
	v_exp_f32_e32 v44, v44
	v_exp_f32_e32 v45, v45
	v_exp_f32_e32 v46, v46
	v_exp_f32_e32 v47, v47
	v_exp_f32_e32 v40, v40
	v_exp_f32_e32 v41, v41
	v_exp_f32_e32 v42, v42
	v_exp_f32_e32 v43, v43
	v_add_f32_e32 v44, 1.0, v44
	v_add_f32_e32 v45, 1.0, v45
	v_add_f32_e32 v46, 1.0, v46
	v_add_f32_e32 v47, 1.0, v47
	v_add_f32_e32 v40, 1.0, v40
	v_add_f32_e32 v41, 1.0, v41
	v_add_f32_e32 v42, 1.0, v42
	v_add_f32_e32 v43, 1.0, v43
	v_rcp_f32_e32 v44, v44
	v_rcp_f32_e32 v45, v45
	v_rcp_f32_e32 v46, v46
	v_rcp_f32_e32 v47, v47
	v_rcp_f32_e32 v40, v40
	v_rcp_f32_e32 v41, v41
	v_rcp_f32_e32 v42, v42
	v_rcp_f32_e32 v43, v43
	s_nop 0
	v_cvt_pk_bf16_f32 v112, v44, v45
	v_cvt_pk_bf16_f32 v113, v46, v47
	v_cvt_pk_bf16_f32 v114, v40, v41
	v_cvt_pk_bf16_f32 v115, v42, v43
	global_store_dwordx4 v[150:151], v[112:115], off
	v_pk_mul_f32 v[36:37], v[36:37], v[178:179] op_sel_hi:[1,0]
	v_pk_mul_f32 v[38:39], v[38:39], v[178:179] op_sel_hi:[1,0]
	v_pk_mul_f32 v[32:33], v[32:33], v[178:179] op_sel_hi:[1,0]
	v_pk_mul_f32 v[34:35], v[34:35], v[178:179] op_sel_hi:[1,0]
; __device__ __forceinline__ unsigned cvt_pk_bf16(float lo, float hi) { unsigned r; asm volatile("v_cvt_pk_bf16_f32 %0, %1, %2" : "=v"(r) : "v"(lo), "v"(hi)); return r; }
; #define GAS __attribute__((address_space(1)))
;     DI void operator()(AccRef acc, const pg8::Unit& u, int wr, int wc, int, int) const {
;     ...
;                 { const float rsk = (kind == 4) ? rs * -1.4426950408889634f : rs; v0 = v0 * rsk; v1 = v1 * rsk; }
;                 if (kind < 2) {
;                     if (rot) {
;                         f32x4 p0, p1;
; #pragma unroll
;                         for (int e = 0; e < 4; ++e) { p0[e] = lane_xor<16>(v0[e]); p1[e] = lane_xor<16>(v1[e]); }
;                         if (fq == 0) { v0 = v0 * c0 - p0 * s0; v1 = v1 * c1 - p1 * s1; }
;                         else if (fq == 1) { v0 = v0 * c0 + p0 * s0; v1 = v1 * c1 + p1 * s1; }
;                     }
;                     v0 = v0 * qs; v1 = v1 * qs;
;                 } else if (kind == 3) {
;                     f32x2 a = pg8::gelu_pk((f32x2){v0[0], v0[1]}), b = pg8::gelu_pk((f32x2){v0[2], v0[3]}), c = pg8::gelu_pk((f32x2){v1[0], v1[1]}), d = pg8::gelu_pk((f32x2){v1[2], v1[3]});
;                     v0 = (f32x4){a.x, a.y, b.x, b.y}; v1 = (f32x4){c.x, c.y, d.x, d.y};
;                 } else if (kind == 4) {
; #pragma unroll
;                     for (int e = 0; e < 4; ++e) { v0[e] = __builtin_amdgcn_rcpf(1.0f + __builtin_amdgcn_exp2f(v0[e])); v1[e] = __builtin_amdgcn_rcpf(1.0f + __builtin_amdgcn_exp2f(v1[e])); }
;                 }
;                 u32x4 w; w.x = cvt_pk_bf16(v0[0], v0[1]); w.y = cvt_pk_bf16(v0[2], v0[3]); w.z = cvt_pk_bf16(v1[0], v1[1]); w.w = cvt_pk_bf16(v1[2], v1[3]);
;                 *(GAS u32x4*)(dummy ? dummy + lane_ * 8 : Z + (size_t)lrow * ldz + col) = w;
	v_exp_f32_e32 v36, v36
	v_exp_f32_e32 v37, v37
	v_exp_f32_e32 v38, v38
	v_exp_f32_e32 v39, v39
	v_exp_f32_e32 v32, v32
	v_exp_f32_e32 v33, v33
	v_exp_f32_e32 v34, v34
	v_exp_f32_e32 v35, v35
	v_add_f32_e32 v36, 1.0, v36
	v_add_f32_e32 v37, 1.0, v37
	v_add_f32_e32 v38, 1.0, v38
	v_add_f32_e32 v39, 1.0, v39
	v_add_f32_e32 v32, 1.0, v32
	v_add_f32_e32 v33, 1.0, v33
	v_add_f32_e32 v34, 1.0, v34
	v_add_f32_e32 v35, 1.0, v35
	v_rcp_f32_e32 v36, v36
	v_rcp_f32_e32 v37, v37
	v_rcp_f32_e32 v38, v38
	v_rcp_f32_e32 v39, v39
	v_rcp_f32_e32 v32, v32
	v_rcp_f32_e32 v33, v33
	v_rcp_f32_e32 v34, v34
	v_rcp_f32_e32 v35, v35
	s_nop 0
	v_cvt_pk_bf16_f32 v116, v36, v37
	v_cvt_pk_bf16_f32 v117, v38, v39
	v_cvt_pk_bf16_f32 v118, v32, v33
	v_cvt_pk_bf16_f32 v119, v34, v35
	global_store_dwordx4 v[150:151], v[116:119], off offset:256
	v_lshl_add_u64 v[146:147], v[150:151], 0, s[2:3]
	v_pk_mul_f32 v[28:29], v[28:29], v[180:181] op_sel_hi:[1,0]
	v_pk_mul_f32 v[30:31], v[30:31], v[180:181] op_sel_hi:[1,0]
	v_pk_mul_f32 v[24:25], v[24:25], v[180:181] op_sel_hi:[1,0]
	v_pk_mul_f32 v[26:27], v[26:27], v[180:181] op_sel_hi:[1,0]
	v_exp_f32_e32 v28, v28
	v_exp_f32_e32 v29, v29
	v_exp_f32_e32 v30, v30
	v_exp_f32_e32 v31, v31
	v_exp_f32_e32 v24, v24
	v_exp_f32_e32 v25, v25
	v_exp_f32_e32 v26, v26
	v_exp_f32_e32 v27, v27
	v_add_f32_e32 v28, 1.0, v28
	v_add_f32_e32 v29, 1.0, v29
	v_add_f32_e32 v30, 1.0, v30
	v_add_f32_e32 v31, 1.0, v31
	v_add_f32_e32 v24, 1.0, v24
	v_add_f32_e32 v25, 1.0, v25
	v_add_f32_e32 v26, 1.0, v26
	v_add_f32_e32 v27, 1.0, v27
	v_rcp_f32_e32 v28, v28
	v_rcp_f32_e32 v29, v29
	v_rcp_f32_e32 v30, v30
	v_rcp_f32_e32 v31, v31
	v_rcp_f32_e32 v24, v24
	v_rcp_f32_e32 v25, v25
	v_rcp_f32_e32 v26, v26
	v_rcp_f32_e32 v27, v27
	s_nop 0
	v_cvt_pk_bf16_f32 v104, v28, v29
	v_cvt_pk_bf16_f32 v105, v30, v31
	v_cvt_pk_bf16_f32 v106, v24, v25
	v_cvt_pk_bf16_f32 v107, v26, v27
	global_store_dwordx4 v[146:147], v[104:107], off
	v_pk_mul_f32 v[20:21], v[20:21], v[180:181] op_sel_hi:[1,0]
	v_pk_mul_f32 v[22:23], v[22:23], v[180:181] op_sel_hi:[1,0]
	v_pk_mul_f32 v[16:17], v[16:17], v[180:181] op_sel_hi:[1,0]
	v_pk_mul_f32 v[18:19], v[18:19], v[180:181] op_sel_hi:[1,0]
	v_exp_f32_e32 v20, v20
	v_exp_f32_e32 v21, v21
	v_exp_f32_e32 v22, v22
	v_exp_f32_e32 v23, v23
	v_exp_f32_e32 v16, v16
	v_exp_f32_e32 v17, v17
	v_exp_f32_e32 v18, v18
	v_exp_f32_e32 v19, v19
	v_add_f32_e32 v20, 1.0, v20
	v_add_f32_e32 v21, 1.0, v21
	v_add_f32_e32 v22, 1.0, v22
	v_add_f32_e32 v23, 1.0, v23
	v_add_f32_e32 v16, 1.0, v16
	v_add_f32_e32 v17, 1.0, v17
	v_add_f32_e32 v18, 1.0, v18
	v_add_f32_e32 v19, 1.0, v19
	v_rcp_f32_e32 v20, v20
	v_rcp_f32_e32 v21, v21
	v_rcp_f32_e32 v22, v22
	v_rcp_f32_e32 v23, v23
	v_rcp_f32_e32 v16, v16
	v_rcp_f32_e32 v17, v17
	v_rcp_f32_e32 v18, v18
	v_rcp_f32_e32 v19, v19
	s_nop 0
	v_cvt_pk_bf16_f32 v108, v20, v21
	v_cvt_pk_bf16_f32 v109, v22, v23
	v_cvt_pk_bf16_f32 v110, v16, v17
	v_cvt_pk_bf16_f32 v111, v18, v19
	global_store_dwordx4 v[146:147], v[108:111], off offset:256
	v_lshl_add_u64 v[150:151], v[146:147], 0, s[2:3]
	v_pk_mul_f32 v[12:13], v[12:13], v[182:183] op_sel_hi:[1,0]
	v_pk_mul_f32 v[14:15], v[14:15], v[182:183] op_sel_hi:[1,0]
	v_pk_mul_f32 v[8:9], v[8:9], v[182:183] op_sel_hi:[1,0]
	v_pk_mul_f32 v[10:11], v[10:11], v[182:183] op_sel_hi:[1,0]
	v_exp_f32_e32 v12, v12
	v_exp_f32_e32 v13, v13
	v_exp_f32_e32 v14, v14
	v_exp_f32_e32 v15, v15
	v_exp_f32_e32 v8, v8
	v_exp_f32_e32 v9, v9
	v_exp_f32_e32 v10, v10
	v_exp_f32_e32 v11, v11
	v_add_f32_e32 v12, 1.0, v12
	v_add_f32_e32 v13, 1.0, v13
	v_add_f32_e32 v14, 1.0, v14
	v_add_f32_e32 v15, 1.0, v15
	v_add_f32_e32 v8, 1.0, v8
	v_add_f32_e32 v9, 1.0, v9
	v_add_f32_e32 v10, 1.0, v10
	v_add_f32_e32 v11, 1.0, v11
	v_rcp_f32_e32 v12, v12
	v_rcp_f32_e32 v13, v13
	v_rcp_f32_e32 v14, v14
	v_rcp_f32_e32 v15, v15
	v_rcp_f32_e32 v8, v8
	v_rcp_f32_e32 v9, v9
	v_rcp_f32_e32 v10, v10
	v_rcp_f32_e32 v11, v11
	s_nop 0
	v_cvt_pk_bf16_f32 v112, v12, v13
	v_cvt_pk_bf16_f32 v113, v14, v15
	v_cvt_pk_bf16_f32 v114, v8, v9
	v_cvt_pk_bf16_f32 v115, v10, v11
	global_store_dwordx4 v[150:151], v[112:115], off
	v_pk_mul_f32 v[4:5], v[4:5], v[182:183] op_sel_hi:[1,0]
	v_pk_mul_f32 v[6:7], v[6:7], v[182:183] op_sel_hi:[1,0]
	v_pk_mul_f32 v[0:1], v[0:1], v[182:183] op_sel_hi:[1,0]
	v_pk_mul_f32 v[2:3], v[2:3], v[182:183] op_sel_hi:[1,0]
	v_exp_f32_e32 v4, v4
	v_exp_f32_e32 v5, v5
	v_exp_f32_e32 v6, v6
	v_exp_f32_e32 v7, v7
	v_exp_f32_e32 v0, v0
	v_exp_f32_e32 v1, v1
	v_exp_f32_e32 v2, v2
	v_exp_f32_e32 v3, v3
	v_add_f32_e32 v4, 1.0, v4
	v_add_f32_e32 v5, 1.0, v5
	v_add_f32_e32 v6, 1.0, v6
	v_add_f32_e32 v7, 1.0, v7
	v_add_f32_e32 v0, 1.0, v0
	v_add_f32_e32 v1, 1.0, v1
	v_add_f32_e32 v2, 1.0, v2
	v_add_f32_e32 v3, 1.0, v3
	v_rcp_f32_e32 v4, v4
	v_rcp_f32_e32 v5, v5
	v_rcp_f32_e32 v6, v6
	v_rcp_f32_e32 v7, v7
	v_rcp_f32_e32 v0, v0
	v_rcp_f32_e32 v1, v1
	v_rcp_f32_e32 v2, v2
	v_rcp_f32_e32 v3, v3
	s_nop 0
	v_cvt_pk_bf16_f32 v116, v4, v5
	v_cvt_pk_bf16_f32 v117, v6, v7
	v_cvt_pk_bf16_f32 v118, v0, v1
	v_cvt_pk_bf16_f32 v119, v2, v3
	global_store_dwordx4 v[150:151], v[116:119], off offset:256
